# route: merge of the two half-row top-16 lists done on packed keys in registers (bitonic top-half merge) instead of a 16-step serial LDS loop
# speedup vs baseline: 1.0106x; 1.0029x over previous
.LBB0_622:
	s_lshl_b32 s8, s2, 15
	s_or_b32 s8, s8, s47
	s_add_u32 s8, s66, s8
	s_addc_u32 s9, s67, 0
	s_lshl_b32 s2, s2, 8
	s_or_b32 s2, s2, s48
	v_lshl_add_u64 v[0:1], v[94:95], 0, s[2:3]
	v_lshl_add_u64 v[28:29], s[8:9], 0, v[92:93]
	v_mov_b32_e32 v113, v93
	v_lshl_add_u64 v[32:33], v[0:1], 0, v[120:121]
	v_lshl_add_u64 v[34:35], v[0:1], 0, v[122:123]
	v_lshl_add_u64 v[36:37], v[0:1], 0, v[124:125]
	v_lshl_add_u64 v[38:39], v[0:1], 0, v[126:127]
	v_lshl_add_u64 v[0:1], v[28:29], 0, v[112:113]
	v_mov_b32_e32 v115, v93
	v_mov_b32_e32 v117, v93
	v_mov_b32_e32 v119, v93
	global_load_dwordx4 v[0:3], v[0:1], off
	s_nop 0
	global_load_dwordx4 v[4:7], v[32:33], off
	global_load_dwordx4 v[8:11], v[34:35], off
	global_load_dwordx4 v[12:15], v[36:37], off
	global_load_dwordx4 v[16:19], v[38:39], off
	v_lshl_add_u64 v[20:21], v[28:29], 0, v[114:115]
	v_lshl_add_u64 v[24:25], v[28:29], 0, v[116:117]
	v_lshl_add_u64 v[28:29], v[28:29], 0, v[118:119]
	global_load_dwordx4 v[28:31], v[28:29], off
	s_nop 0
	global_load_dwordx4 v[20:23], v[20:21], off
	s_nop 0
	global_load_dwordx4 v[24:27], v[24:25], off
	s_barrier
	s_waitcnt vmcnt(6)
	ds_write_b128 v128, v[4:7]
	s_waitcnt vmcnt(2)
	ds_write_b128 v128, v[28:31] offset:18432
	ds_write_b128 v128, v[8:11] offset:4608
	s_waitcnt vmcnt(0)
	ds_write_b128 v128, v[24:27] offset:23040
	ds_write_b128 v128, v[12:15] offset:9216
	ds_write_b128 v128, v[20:23] offset:27648
	ds_write_b128 v128, v[16:19] offset:13824
	ds_write_b128 v128, v[0:3] offset:32256
	v_lshl_add_u64 v[0:1], s[8:9], 0, v[112:113]
	v_lshl_add_u64 v[0:1], v[0:1], 0, v[92:93]
	s_waitcnt lgkmcnt(0)
	s_barrier
	global_load_dwordx4 v[64:67], v[0:1], off offset:128
	global_load_dwordx4 v[80:83], v[32:33], off offset:128
	global_load_dwordx4 v[76:79], v[34:35], off offset:128
	global_load_dwordx4 v[72:75], v[36:37], off offset:128
	global_load_dwordx4 v[68:71], v[38:39], off offset:128
	v_lshl_add_u64 v[0:1], s[8:9], 0, v[114:115]
	v_lshl_add_u64 v[0:1], v[0:1], 0, v[92:93]
	global_load_dwordx4 v[84:87], v[0:1], off offset:128
	v_lshl_add_u64 v[0:1], s[8:9], 0, v[116:117]
	v_lshl_add_u64 v[0:1], v[0:1], 0, v[92:93]
	global_load_dwordx4 v[88:91], v[0:1], off offset:128
	v_lshl_add_u64 v[0:1], s[8:9], 0, v[118:119]
	v_lshl_add_u64 v[0:1], v[0:1], 0, v[92:93]
	global_load_dwordx4 v[180:183], v[0:1], off offset:128
	ds_read_b128 v[0:3], v130 offset:18432
	ds_read_b128 v[4:7], v129
	ds_read_b128 v[8:11], v130 offset:23040
	s_waitcnt lgkmcnt(1)
	v_mfma_f32_32x32x16_bf16 v[48:63], v[0:3], v[4:7], 0
	s_waitcnt lgkmcnt(0)
	v_mfma_f32_32x32x16_bf16 v[32:47], v[8:11], v[4:7], 0
	ds_read_b128 v[4:7], v129 offset:4608
	ds_read_b128 v[184:187], v130 offset:18464
	ds_read_b128 v[188:191], v129 offset:32
	ds_read_b128 v[192:195], v130 offset:23072
	s_waitcnt lgkmcnt(3)
	v_mfma_f32_32x32x16_bf16 v[16:31], v[0:3], v[4:7], 0
	v_mfma_f32_32x32x16_bf16 v[0:15], v[8:11], v[4:7], 0
	s_waitcnt lgkmcnt(1)
	v_mfma_f32_32x32x16_bf16 v[48:63], v[184:187], v[188:191], v[48:63]
	s_waitcnt lgkmcnt(0)
	v_mfma_f32_32x32x16_bf16 v[32:47], v[192:195], v[188:191], v[32:47]
	ds_read_b128 v[188:191], v129 offset:4640
	s_waitcnt lgkmcnt(0)
	v_mfma_f32_32x32x16_bf16 v[16:31], v[184:187], v[188:191], v[16:31]
	v_mfma_f32_32x32x16_bf16 v[0:15], v[192:195], v[188:191], v[0:15]
	ds_read_b128 v[184:187], v130 offset:18496
	ds_read_b128 v[188:191], v129 offset:64
	ds_read_b128 v[192:195], v130 offset:23104
	s_waitcnt lgkmcnt(1)
	v_mfma_f32_32x32x16_bf16 v[48:63], v[184:187], v[188:191], v[48:63]
	s_waitcnt lgkmcnt(0)
	v_mfma_f32_32x32x16_bf16 v[32:47], v[192:195], v[188:191], v[32:47]
	ds_read_b128 v[188:191], v129 offset:4672
	s_waitcnt lgkmcnt(0)
	v_mfma_f32_32x32x16_bf16 v[16:31], v[184:187], v[188:191], v[16:31]
	v_mfma_f32_32x32x16_bf16 v[0:15], v[192:195], v[188:191], v[0:15]
	ds_read_b128 v[184:187], v130 offset:18528
	ds_read_b128 v[188:191], v129 offset:96
	ds_read_b128 v[192:195], v130 offset:23136
	s_waitcnt lgkmcnt(1)
	v_mfma_f32_32x32x16_bf16 v[48:63], v[184:187], v[188:191], v[48:63]
	s_waitcnt lgkmcnt(0)
	v_mfma_f32_32x32x16_bf16 v[32:47], v[192:195], v[188:191], v[32:47]
	ds_read_b128 v[188:191], v129 offset:4704
	s_waitcnt lgkmcnt(0)
	s_barrier
	s_waitcnt vmcnt(6)
	ds_write_b128 v128, v[80:83]
	s_waitcnt vmcnt(0)
	ds_write_b128 v128, v[180:183] offset:18432
	ds_write_b128 v128, v[76:79] offset:4608
	ds_write_b128 v128, v[88:91] offset:23040
	ds_write_b128 v128, v[72:75] offset:9216
	ds_write_b128 v128, v[84:87] offset:27648
	ds_write_b128 v128, v[68:71] offset:13824
	ds_write_b128 v128, v[64:67] offset:32256
	s_waitcnt lgkmcnt(0)
	v_mfma_f32_32x32x16_bf16 v[16:31], v[184:187], v[188:191], v[16:31]
	s_barrier
	v_mfma_f32_32x32x16_bf16 v[0:15], v[192:195], v[188:191], v[0:15]
	ds_read_b128 v[64:67], v130 offset:18432
	ds_read_b128 v[68:71], v129
	ds_read_b128 v[72:75], v129 offset:32
	ds_read_b128 v[76:79], v130 offset:18464
	ds_read_b128 v[80:83], v130 offset:23040
	ds_read_b128 v[84:87], v130 offset:23072
	s_waitcnt lgkmcnt(4)
	v_mfma_f32_32x32x16_bf16 v[48:63], v[64:67], v[68:71], v[48:63]
	s_waitcnt lgkmcnt(2)
	v_mfma_f32_32x32x16_bf16 v[48:63], v[76:79], v[72:75], v[48:63]
	s_waitcnt lgkmcnt(1)
	v_mfma_f32_32x32x16_bf16 v[32:47], v[80:83], v[68:71], v[32:47]
	ds_read_b128 v[68:71], v130 offset:18496
	ds_read_b128 v[88:91], v129 offset:64
	ds_read_b128 v[180:183], v129 offset:4608
	ds_read_b128 v[184:187], v129 offset:4640
	ds_read_b128 v[188:191], v129 offset:96
	ds_read_b128 v[192:195], v130 offset:18528
	ds_read_b128 v[196:199], v129 offset:4672
	ds_read_b128 v[200:203], v129 offset:4704
	ds_read_b128 v[210:213], v130 offset:23104
	ds_read_b128 v[214:217], v130 offset:23136
	s_waitcnt lgkmcnt(0)
	s_barrier
	v_mfma_f32_32x32x16_bf16 v[48:63], v[68:71], v[88:91], v[48:63]
	v_mfma_f32_32x32x16_bf16 v[48:63], v[192:195], v[188:191], v[48:63]
	v_mfma_f32_32x32x16_bf16 v[16:31], v[64:67], v[180:183], v[16:31]
	s_nop 10
	v_not_b32_e32 v113, v48
	v_or_b32_e32 v115, 0x80000000, v48
	v_and_b32_e32 v219, 0x7fffffff, v50
	v_and_b32_e32 v218, 0x7fffffff, v49
	v_cmp_gt_i32_e32 vcc, 0, v48
	v_xor_b32_e32 v117, -1, v50
	v_pk_add_f32 v[218:219], v[218:219], 0 neg_lo:[1,1] neg_hi:[1,1]
	v_cndmask_b32_e32 v48, v115, v113, vcc
	v_cmp_gt_i32_e32 vcc, 0, v50
	v_xor_b32_e32 v119, -1, v49
	v_not_b32_e32 v64, v51
	v_cndmask_b32_e32 v50, v219, v117, vcc
	v_cmp_gt_i32_e32 vcc, 0, v49
	v_or_b32_e32 v65, 0x80000000, v51
	v_and_b32_e32 v50, 0xffffff80, v50
	v_cndmask_b32_e32 v49, v218, v119, vcc
	v_cmp_gt_i32_e32 vcc, 0, v51
	v_and_b32_e32 v49, 0xffffff80, v49
	v_and_b32_e32 v48, 0xffffff80, v48
	v_cndmask_b32_e32 v51, v65, v64, vcc
	v_and_b32_e32 v51, 0xffffff80, v51
	v_sub_u32_e32 v49, v49, v96
	v_sub_u32_e32 v50, v50, v97
	v_sub_u32_e32 v51, v51, v96
	v_bitop3_b32 v48, v48, s19, v96 bitop3:0x36
	v_add_u32_e32 v50, 0x7d, v50
	v_add_u32_e32 v49, 0x7e, v49
	v_add_u32_e32 v51, 0x7c, v51
	ds_write_b128 v136, v[48:51]
	v_not_b32_e32 v48, v52
	v_or_b32_e32 v49, 0x80000000, v52
	v_cmp_gt_i32_e32 vcc, 0, v52
	v_and_b32_e32 v51, 0x7fffffff, v54
	v_and_b32_e32 v50, 0x7fffffff, v53
	v_cndmask_b32_e32 v48, v49, v48, vcc
	v_xor_b32_e32 v49, -1, v54
	v_pk_add_f32 v[50:51], v[50:51], 0 neg_lo:[1,1] neg_hi:[1,1]
	v_cmp_gt_i32_e32 vcc, 0, v54
	v_xor_b32_e32 v52, -1, v53
	v_and_b32_e32 v48, 0xffffff80, v48
	v_cndmask_b32_e32 v49, v51, v49, vcc
	v_cmp_gt_i32_e32 vcc, 0, v53
	v_and_b32_e32 v49, 0xffffff80, v49
	v_sub_u32_e32 v49, v49, v99
	v_cndmask_b32_e32 v50, v50, v52, vcc
	v_and_b32_e32 v50, 0xffffff80, v50
	v_sub_u32_e32 v51, v50, v98
	v_add_u32_e32 v50, 0x7d, v49
	v_add_u32_e32 v49, 0x7e, v51
	v_not_b32_e32 v51, v55
	v_or_b32_e32 v52, 0x80000000, v55
	v_cmp_gt_i32_e32 vcc, 0, v55
	v_mfma_f32_32x32x16_bf16 v[32:47], v[84:87], v[72:75], v[32:47]
	v_bitop3_b32 v48, v48, s21, v96 bitop3:0x36
	v_cndmask_b32_e32 v51, v52, v51, vcc
	v_and_b32_e32 v51, 0xffffff80, v51
	v_sub_u32_e32 v51, v51, v98
	v_add_u32_e32 v51, 0x7c, v51
	ds_write_b128 v137, v[48:51]
	v_not_b32_e32 v48, v56
	v_or_b32_e32 v49, 0x80000000, v56
	v_cmp_gt_i32_e32 vcc, 0, v56
	v_and_b32_e32 v51, 0x7fffffff, v58
	v_and_b32_e32 v50, 0x7fffffff, v57
	v_cndmask_b32_e32 v48, v49, v48, vcc
	v_xor_b32_e32 v49, -1, v58
	v_pk_add_f32 v[50:51], v[50:51], 0 neg_lo:[1,1] neg_hi:[1,1]
	v_cmp_gt_i32_e32 vcc, 0, v58
	v_xor_b32_e32 v52, -1, v57
	v_mfma_f32_32x32x16_bf16 v[32:47], v[210:213], v[88:91], v[32:47]
	v_cndmask_b32_e32 v49, v51, v49, vcc
	v_cmp_gt_i32_e32 vcc, 0, v57
	v_and_b32_e32 v49, 0xffffff80, v49
	v_sub_u32_e32 v49, v49, v101
	v_cndmask_b32_e32 v50, v50, v52, vcc
	v_and_b32_e32 v50, 0xffffff80, v50
	v_sub_u32_e32 v51, v50, v100
	v_add_u32_e32 v50, 0x7d, v49
	v_add_u32_e32 v49, 0x7e, v51
	v_not_b32_e32 v51, v59
	v_or_b32_e32 v52, 0x80000000, v59
	v_cmp_gt_i32_e32 vcc, 0, v59
	v_and_b32_e32 v48, 0xffffff80, v48
	v_bitop3_b32 v48, v48, s22, v96 bitop3:0x36
	v_cndmask_b32_e32 v51, v52, v51, vcc
	v_and_b32_e32 v51, 0xffffff80, v51
	v_sub_u32_e32 v51, v51, v100
	v_add_u32_e32 v51, 0x7c, v51
	ds_write_b128 v138, v[48:51]
	v_not_b32_e32 v48, v60
	v_or_b32_e32 v49, 0x80000000, v60
	v_cmp_gt_i32_e32 vcc, 0, v60
	v_and_b32_e32 v51, 0x7fffffff, v62
	v_and_b32_e32 v50, 0x7fffffff, v61
	v_cndmask_b32_e32 v48, v49, v48, vcc
	v_xor_b32_e32 v49, -1, v62
	v_pk_add_f32 v[50:51], v[50:51], 0 neg_lo:[1,1] neg_hi:[1,1]
	v_cmp_gt_i32_e32 vcc, 0, v62
	v_xor_b32_e32 v52, -1, v61
	v_mfma_f32_32x32x16_bf16 v[32:47], v[214:217], v[188:191], v[32:47]
	v_cndmask_b32_e32 v49, v51, v49, vcc
	v_cmp_gt_i32_e32 vcc, 0, v61
	v_and_b32_e32 v49, 0xffffff80, v49
	v_sub_u32_e32 v49, v49, v103
	v_cndmask_b32_e32 v50, v50, v52, vcc
	v_and_b32_e32 v50, 0xffffff80, v50
	v_sub_u32_e32 v51, v50, v102
	v_add_u32_e32 v50, 0x7d, v49
	v_add_u32_e32 v49, 0x7e, v51
	v_not_b32_e32 v51, v63
	v_or_b32_e32 v52, 0x80000000, v63
	v_cmp_gt_i32_e32 vcc, 0, v63
	v_and_b32_e32 v48, 0xffffff80, v48
	v_bitop3_b32 v48, v48, s23, v96 bitop3:0x36
	v_cndmask_b32_e32 v51, v52, v51, vcc
	v_and_b32_e32 v51, 0xffffff80, v51
	v_sub_u32_e32 v51, v51, v102
	v_add_u32_e32 v51, 0x7c, v51
	ds_write_b128 v139, v[48:51]
	v_not_b32_e32 v48, v32
	v_or_b32_e32 v49, 0x80000000, v32
	v_cmp_gt_i32_e32 vcc, 0, v32
	v_xor_b32_e32 v50, -1, v34
	v_xor_b32_e32 v51, -1, v33
	v_cndmask_b32_e32 v32, v49, v48, vcc
	v_and_b32_e32 v49, 0x7fffffff, v34
	v_and_b32_e32 v48, 0x7fffffff, v33
	v_pk_add_f32 v[48:49], v[48:49], 0 neg_lo:[1,1] neg_hi:[1,1]
	v_cmp_gt_i32_e32 vcc, 0, v34
	v_and_b32_e32 v32, 0xffffff80, v32
	v_bitop3_b32 v32, v32, s16, v96 bitop3:0x36
	v_cndmask_b32_e32 v34, v49, v50, vcc
	v_cmp_gt_i32_e32 vcc, 0, v33
	v_or_b32_e32 v49, 0x80000000, v35
	v_and_b32_e32 v34, 0xffffff80, v34
	v_cndmask_b32_e32 v33, v48, v51, vcc
	v_not_b32_e32 v48, v35
	v_cmp_gt_i32_e32 vcc, 0, v35
	v_and_b32_e32 v33, 0xffffff80, v33
	v_sub_u32_e32 v33, v33, v104
	v_cndmask_b32_e32 v35, v49, v48, vcc
	v_and_b32_e32 v35, 0xffffff80, v35
	v_sub_u32_e32 v34, v34, v105
	v_sub_u32_e32 v35, v35, v104
	v_add_u32_e32 v34, 0x7d, v34
	v_add_u32_e32 v33, 0x7e, v33
	v_add_u32_e32 v35, 0x7c, v35
	ds_write_b128 v140, v[32:35]
	v_not_b32_e32 v32, v36
	v_or_b32_e32 v33, 0x80000000, v36
	v_cmp_gt_i32_e32 vcc, 0, v36
	v_and_b32_e32 v35, 0x7fffffff, v38
	v_and_b32_e32 v34, 0x7fffffff, v37
	v_cndmask_b32_e32 v32, v33, v32, vcc
	v_xor_b32_e32 v33, -1, v38
	v_pk_add_f32 v[34:35], v[34:35], 0 neg_lo:[1,1] neg_hi:[1,1]
	v_cmp_gt_i32_e32 vcc, 0, v38
	v_xor_b32_e32 v36, -1, v37
	v_mfma_f32_32x32x16_bf16 v[16:31], v[76:79], v[184:187], v[16:31]
	v_cndmask_b32_e32 v33, v35, v33, vcc
	v_cmp_gt_i32_e32 vcc, 0, v37
	v_and_b32_e32 v33, 0xffffff80, v33
	v_sub_u32_e32 v33, v33, v107
	v_cndmask_b32_e32 v34, v34, v36, vcc
	v_and_b32_e32 v34, 0xffffff80, v34
	v_sub_u32_e32 v35, v34, v106
	v_add_u32_e32 v34, 0x7d, v33
	v_add_u32_e32 v33, 0x7e, v35
	v_not_b32_e32 v35, v39
	v_or_b32_e32 v36, 0x80000000, v39
	v_cmp_gt_i32_e32 vcc, 0, v39
	v_and_b32_e32 v32, 0xffffff80, v32
	v_bitop3_b32 v32, v32, s24, v96 bitop3:0x36
	v_cndmask_b32_e32 v35, v36, v35, vcc
	v_and_b32_e32 v35, 0xffffff80, v35
	v_sub_u32_e32 v35, v35, v106
	v_add_u32_e32 v35, 0x7c, v35
	ds_write_b128 v141, v[32:35]
	v_not_b32_e32 v32, v40
	v_or_b32_e32 v33, 0x80000000, v40
	v_cmp_gt_i32_e32 vcc, 0, v40
	v_and_b32_e32 v35, 0x7fffffff, v42
	v_and_b32_e32 v34, 0x7fffffff, v41
	v_cndmask_b32_e32 v32, v33, v32, vcc
	v_xor_b32_e32 v33, -1, v42
	v_pk_add_f32 v[34:35], v[34:35], 0 neg_lo:[1,1] neg_hi:[1,1]
	v_cmp_gt_i32_e32 vcc, 0, v42
	v_xor_b32_e32 v36, -1, v41
	v_mfma_f32_32x32x16_bf16 v[16:31], v[68:71], v[196:199], v[16:31]
	v_cndmask_b32_e32 v33, v35, v33, vcc
	v_cmp_gt_i32_e32 vcc, 0, v41
	v_and_b32_e32 v33, 0xffffff80, v33
	v_sub_u32_e32 v33, v33, v109
	v_cndmask_b32_e32 v34, v34, v36, vcc
	v_and_b32_e32 v34, 0xffffff80, v34
	v_sub_u32_e32 v35, v34, v108
	v_add_u32_e32 v34, 0x7d, v33
	v_add_u32_e32 v33, 0x7e, v35
	v_not_b32_e32 v35, v43
	v_or_b32_e32 v36, 0x80000000, v43
	v_cmp_gt_i32_e32 vcc, 0, v43
	v_and_b32_e32 v32, 0xffffff80, v32
	v_bitop3_b32 v32, v32, s25, v96 bitop3:0x36
	v_cndmask_b32_e32 v35, v36, v35, vcc
	v_and_b32_e32 v35, 0xffffff80, v35
	v_sub_u32_e32 v35, v35, v108
	v_add_u32_e32 v35, 0x7c, v35
	ds_write_b128 v142, v[32:35]
	v_not_b32_e32 v32, v44
	v_or_b32_e32 v33, 0x80000000, v44
	v_cmp_gt_i32_e32 vcc, 0, v44
	v_and_b32_e32 v35, 0x7fffffff, v46
	v_and_b32_e32 v34, 0x7fffffff, v45
	v_cndmask_b32_e32 v32, v33, v32, vcc
	v_xor_b32_e32 v33, -1, v46
	v_pk_add_f32 v[34:35], v[34:35], 0 neg_lo:[1,1] neg_hi:[1,1]
	v_cmp_gt_i32_e32 vcc, 0, v46
	v_xor_b32_e32 v36, -1, v45
	v_mfma_f32_32x32x16_bf16 v[16:31], v[192:195], v[200:203], v[16:31]
	v_cndmask_b32_e32 v33, v35, v33, vcc
	v_cmp_gt_i32_e32 vcc, 0, v45
	v_and_b32_e32 v33, 0xffffff80, v33
	v_sub_u32_e32 v33, v33, v111
	v_cndmask_b32_e32 v34, v34, v36, vcc
	v_and_b32_e32 v34, 0xffffff80, v34
	v_sub_u32_e32 v35, v34, v110
	v_add_u32_e32 v34, 0x7d, v33
	v_add_u32_e32 v33, 0x7e, v35
	v_not_b32_e32 v35, v47
	v_or_b32_e32 v36, 0x80000000, v47
	v_cmp_gt_i32_e32 vcc, 0, v47
	v_and_b32_e32 v32, 0xffffff80, v32
	v_bitop3_b32 v32, v32, s26, v96 bitop3:0x36
	v_cndmask_b32_e32 v35, v36, v35, vcc
	v_and_b32_e32 v35, 0xffffff80, v35
	v_sub_u32_e32 v35, v35, v110
	v_add_u32_e32 v35, 0x7c, v35
	ds_write_b128 v143, v[32:35]
	v_not_b32_e32 v32, v16
	v_or_b32_e32 v33, 0x80000000, v16
	v_cmp_gt_i32_e32 vcc, 0, v16
	v_xor_b32_e32 v34, -1, v18
	v_xor_b32_e32 v35, -1, v17
	v_cndmask_b32_e32 v16, v33, v32, vcc
	v_and_b32_e32 v33, 0x7fffffff, v18
	v_and_b32_e32 v32, 0x7fffffff, v17
	v_pk_add_f32 v[32:33], v[32:33], 0 neg_lo:[1,1] neg_hi:[1,1]
	v_cmp_gt_i32_e32 vcc, 0, v18
	v_and_b32_e32 v16, 0xffffff80, v16
	v_bitop3_b32 v16, v16, s19, v96 bitop3:0x36
	v_cndmask_b32_e32 v18, v33, v34, vcc
	v_cmp_gt_i32_e32 vcc, 0, v17
	v_or_b32_e32 v33, 0x80000000, v19
	v_and_b32_e32 v18, 0xffffff80, v18
	v_cndmask_b32_e32 v17, v32, v35, vcc
	v_not_b32_e32 v32, v19
	v_cmp_gt_i32_e32 vcc, 0, v19
	v_and_b32_e32 v17, 0xffffff80, v17
	v_sub_u32_e32 v17, v17, v96
	v_cndmask_b32_e32 v19, v33, v32, vcc
	v_and_b32_e32 v19, 0xffffff80, v19
	v_sub_u32_e32 v18, v18, v97
	v_sub_u32_e32 v19, v19, v96
	v_add_u32_e32 v18, 0x7d, v18
	v_add_u32_e32 v17, 0x7e, v17
	v_add_u32_e32 v19, 0x7c, v19
	ds_write_b128 v136, v[16:19] offset:16384
	v_not_b32_e32 v16, v20
	v_or_b32_e32 v17, 0x80000000, v20
	v_cmp_gt_i32_e32 vcc, 0, v20
	v_and_b32_e32 v19, 0x7fffffff, v22
	v_and_b32_e32 v18, 0x7fffffff, v21
	v_mfma_f32_32x32x16_bf16 v[0:15], v[80:83], v[180:183], v[0:15]
	v_cndmask_b32_e32 v16, v17, v16, vcc
	v_xor_b32_e32 v17, -1, v22
	v_add_f32_e64 v18, -v18, neg(0)
	v_add_f32_e64 v19, -v19, neg(0)
	v_cmp_gt_i32_e32 vcc, 0, v22
	v_xor_b32_e32 v20, -1, v21
	v_and_b32_e32 v16, 0xffffff80, v16
	v_cndmask_b32_e32 v17, v19, v17, vcc
	v_cmp_gt_i32_e32 vcc, 0, v21
	v_and_b32_e32 v17, 0xffffff80, v17
	v_sub_u32_e32 v17, v17, v99
	v_cndmask_b32_e32 v18, v18, v20, vcc
	v_and_b32_e32 v18, 0xffffff80, v18
	v_sub_u32_e32 v19, v18, v98
	v_add_u32_e32 v18, 0x7d, v17
	v_add_u32_e32 v17, 0x7e, v19
	v_not_b32_e32 v19, v23
	v_or_b32_e32 v20, 0x80000000, v23
	v_cmp_gt_i32_e32 vcc, 0, v23
	v_mfma_f32_32x32x16_bf16 v[0:15], v[84:87], v[184:187], v[0:15]
	v_bitop3_b32 v16, v16, s21, v96 bitop3:0x36
	v_cndmask_b32_e32 v19, v20, v19, vcc
	v_and_b32_e32 v19, 0xffffff80, v19
	v_sub_u32_e32 v19, v19, v98
	v_add_u32_e32 v19, 0x7c, v19
	ds_write_b128 v137, v[16:19] offset:16384
	v_not_b32_e32 v16, v24
	v_or_b32_e32 v17, 0x80000000, v24
	v_cmp_gt_i32_e32 vcc, 0, v24
	v_and_b32_e32 v19, 0x7fffffff, v26
	v_and_b32_e32 v18, 0x7fffffff, v25
	v_cndmask_b32_e32 v16, v17, v16, vcc
	v_xor_b32_e32 v17, -1, v26
	v_pk_add_f32 v[18:19], v[18:19], 0 neg_lo:[1,1] neg_hi:[1,1]
	v_cmp_gt_i32_e32 vcc, 0, v26
	v_xor_b32_e32 v20, -1, v25
	v_mfma_f32_32x32x16_bf16 v[0:15], v[210:213], v[196:199], v[0:15]
	v_cndmask_b32_e32 v17, v19, v17, vcc
	v_cmp_gt_i32_e32 vcc, 0, v25
	v_and_b32_e32 v17, 0xffffff80, v17
	v_sub_u32_e32 v17, v17, v101
	v_cndmask_b32_e32 v18, v18, v20, vcc
	v_and_b32_e32 v18, 0xffffff80, v18
	v_sub_u32_e32 v19, v18, v100
	v_add_u32_e32 v18, 0x7d, v17
	v_add_u32_e32 v17, 0x7e, v19
	v_not_b32_e32 v19, v27
	v_or_b32_e32 v20, 0x80000000, v27
	v_cmp_gt_i32_e32 vcc, 0, v27
	v_and_b32_e32 v16, 0xffffff80, v16
	v_bitop3_b32 v16, v16, s22, v96 bitop3:0x36
	v_cndmask_b32_e32 v19, v20, v19, vcc
	v_and_b32_e32 v19, 0xffffff80, v19
	v_sub_u32_e32 v19, v19, v100
	v_add_u32_e32 v19, 0x7c, v19
	ds_write_b128 v138, v[16:19] offset:16384
	v_not_b32_e32 v16, v28
	v_or_b32_e32 v17, 0x80000000, v28
	v_cmp_gt_i32_e32 vcc, 0, v28
	v_and_b32_e32 v19, 0x7fffffff, v30
	v_and_b32_e32 v18, 0x7fffffff, v29
	v_cndmask_b32_e32 v16, v17, v16, vcc
	v_xor_b32_e32 v17, -1, v30
	v_pk_add_f32 v[18:19], v[18:19], 0 neg_lo:[1,1] neg_hi:[1,1]
	v_cmp_gt_i32_e32 vcc, 0, v30
	v_xor_b32_e32 v20, -1, v29
	v_mfma_f32_32x32x16_bf16 v[0:15], v[214:217], v[200:203], v[0:15]
	v_cndmask_b32_e32 v17, v19, v17, vcc
	v_cmp_gt_i32_e32 vcc, 0, v29
	v_and_b32_e32 v17, 0xffffff80, v17
	v_sub_u32_e32 v17, v17, v103
	v_cndmask_b32_e32 v18, v18, v20, vcc
	v_and_b32_e32 v18, 0xffffff80, v18
	v_sub_u32_e32 v19, v18, v102
	v_add_u32_e32 v18, 0x7d, v17
	v_add_u32_e32 v17, 0x7e, v19
	v_not_b32_e32 v19, v31
	v_or_b32_e32 v20, 0x80000000, v31
	v_cmp_gt_i32_e32 vcc, 0, v31
	v_and_b32_e32 v16, 0xffffff80, v16
	v_bitop3_b32 v16, v16, s23, v96 bitop3:0x36
	v_cndmask_b32_e32 v19, v20, v19, vcc
	v_and_b32_e32 v19, 0xffffff80, v19
	v_sub_u32_e32 v19, v19, v102
	v_add_u32_e32 v19, 0x7c, v19
	ds_write_b128 v139, v[16:19] offset:16384
	v_not_b32_e32 v16, v0
	v_or_b32_e32 v17, 0x80000000, v0
	v_cmp_gt_i32_e32 vcc, 0, v0
	v_xor_b32_e32 v18, -1, v2
	v_xor_b32_e32 v19, -1, v1
	v_cndmask_b32_e32 v0, v17, v16, vcc
	v_and_b32_e32 v17, 0x7fffffff, v2
	v_and_b32_e32 v16, 0x7fffffff, v1
	v_pk_add_f32 v[16:17], v[16:17], 0 neg_lo:[1,1] neg_hi:[1,1]
	v_cmp_gt_i32_e32 vcc, 0, v2
	v_and_b32_e32 v0, 0xffffff80, v0
	v_bitop3_b32 v0, v0, s16, v96 bitop3:0x36
	v_cndmask_b32_e32 v2, v17, v18, vcc
	v_cmp_gt_i32_e32 vcc, 0, v1
	v_or_b32_e32 v17, 0x80000000, v3
	v_and_b32_e32 v2, 0xffffff80, v2
	v_cndmask_b32_e32 v1, v16, v19, vcc
	v_not_b32_e32 v16, v3
	v_cmp_gt_i32_e32 vcc, 0, v3
	v_and_b32_e32 v1, 0xffffff80, v1
	v_sub_u32_e32 v1, v1, v104
	v_cndmask_b32_e32 v3, v17, v16, vcc
	v_and_b32_e32 v3, 0xffffff80, v3
	v_sub_u32_e32 v2, v2, v105
	v_sub_u32_e32 v3, v3, v104
	v_add_u32_e32 v2, 0x7d, v2
	v_add_u32_e32 v1, 0x7e, v1
	v_add_u32_e32 v3, 0x7c, v3
	ds_write_b128 v140, v[0:3] offset:16384
	v_not_b32_e32 v0, v4
	v_or_b32_e32 v1, 0x80000000, v4
	v_cmp_gt_i32_e32 vcc, 0, v4
	v_and_b32_e32 v3, 0x7fffffff, v6
	v_and_b32_e32 v2, 0x7fffffff, v5
	v_cndmask_b32_e32 v0, v1, v0, vcc
	v_xor_b32_e32 v1, -1, v6
	v_pk_add_f32 v[2:3], v[2:3], 0 neg_lo:[1,1] neg_hi:[1,1]
	v_cmp_gt_i32_e32 vcc, 0, v6
	v_xor_b32_e32 v4, -1, v5
	v_and_b32_e32 v0, 0xffffff80, v0
	v_cndmask_b32_e32 v1, v3, v1, vcc
	v_cmp_gt_i32_e32 vcc, 0, v5
	v_and_b32_e32 v1, 0xffffff80, v1
	v_sub_u32_e32 v1, v1, v107
	v_cndmask_b32_e32 v2, v2, v4, vcc
	v_and_b32_e32 v2, 0xffffff80, v2
	v_sub_u32_e32 v3, v2, v106
	v_add_u32_e32 v2, 0x7d, v1
	v_add_u32_e32 v1, 0x7e, v3
	v_not_b32_e32 v3, v7
	v_or_b32_e32 v4, 0x80000000, v7
	v_cmp_gt_i32_e32 vcc, 0, v7
	v_bitop3_b32 v0, v0, s24, v96 bitop3:0x36
	s_nop 0
	v_cndmask_b32_e32 v3, v4, v3, vcc
	v_and_b32_e32 v3, 0xffffff80, v3
	v_sub_u32_e32 v3, v3, v106
	v_add_u32_e32 v3, 0x7c, v3
	ds_write_b128 v141, v[0:3] offset:16384
	v_not_b32_e32 v0, v8
	v_or_b32_e32 v1, 0x80000000, v8
	v_cmp_gt_i32_e32 vcc, 0, v8
	v_and_b32_e32 v3, 0x7fffffff, v10
	v_and_b32_e32 v2, 0x7fffffff, v9
	v_cndmask_b32_e32 v0, v1, v0, vcc
	v_xor_b32_e32 v1, -1, v10
	v_pk_add_f32 v[2:3], v[2:3], 0 neg_lo:[1,1] neg_hi:[1,1]
	v_cmp_gt_i32_e32 vcc, 0, v10
	v_xor_b32_e32 v4, -1, v9
	v_and_b32_e32 v0, 0xffffff80, v0
	v_cndmask_b32_e32 v1, v3, v1, vcc
	v_cmp_gt_i32_e32 vcc, 0, v9
	v_and_b32_e32 v1, 0xffffff80, v1
	v_sub_u32_e32 v1, v1, v109
	v_cndmask_b32_e32 v2, v2, v4, vcc
	v_and_b32_e32 v2, 0xffffff80, v2
	v_sub_u32_e32 v3, v2, v108
	v_add_u32_e32 v2, 0x7d, v1
	v_add_u32_e32 v1, 0x7e, v3
	v_not_b32_e32 v3, v11
	v_or_b32_e32 v4, 0x80000000, v11
	v_cmp_gt_i32_e32 vcc, 0, v11
	v_bitop3_b32 v0, v0, s25, v96 bitop3:0x36
	s_nop 0
	v_cndmask_b32_e32 v3, v4, v3, vcc
	v_and_b32_e32 v3, 0xffffff80, v3
	v_sub_u32_e32 v3, v3, v108
	v_add_u32_e32 v3, 0x7c, v3
	ds_write_b128 v142, v[0:3] offset:16384
	v_not_b32_e32 v0, v12
	v_or_b32_e32 v1, 0x80000000, v12
	v_cmp_gt_i32_e32 vcc, 0, v12
	v_and_b32_e32 v3, 0x7fffffff, v14
	v_and_b32_e32 v2, 0x7fffffff, v13
	v_cndmask_b32_e32 v0, v1, v0, vcc
	v_xor_b32_e32 v1, -1, v14
	v_pk_add_f32 v[2:3], v[2:3], 0 neg_lo:[1,1] neg_hi:[1,1]
	v_cmp_gt_i32_e32 vcc, 0, v14
	v_xor_b32_e32 v4, -1, v13
	v_and_b32_e32 v0, 0xffffff80, v0
	v_cndmask_b32_e32 v1, v3, v1, vcc
	v_cmp_gt_i32_e32 vcc, 0, v13
	v_and_b32_e32 v1, 0xffffff80, v1
	v_sub_u32_e32 v1, v1, v111
	v_cndmask_b32_e32 v2, v2, v4, vcc
	v_and_b32_e32 v2, 0xffffff80, v2
	v_sub_u32_e32 v3, v2, v110
	v_add_u32_e32 v2, 0x7d, v1
	v_add_u32_e32 v1, 0x7e, v3
	v_not_b32_e32 v3, v15
	v_or_b32_e32 v4, 0x80000000, v15
	v_cmp_gt_i32_e32 vcc, 0, v15
	v_bitop3_b32 v0, v0, s26, v96 bitop3:0x36
	s_nop 0
	v_cndmask_b32_e32 v3, v4, v3, vcc
	v_and_b32_e32 v3, 0xffffff80, v3
	v_sub_u32_e32 v3, v3, v110
	v_add_u32_e32 v3, 0x7c, v3
	ds_write_b128 v143, v[0:3] offset:16384
	s_waitcnt lgkmcnt(0)
	s_barrier
	ds_read_b128 v[0:3], v144
	ds_read_b128 v[4:7], v145
	ds_read_b128 v[8:11], v146
	ds_read_b128 v[12:15], v147
	ds_read_b128 v[16:19], v149
	ds_read_b128 v[20:23], v150
	ds_read_b128 v[24:27], v151
	ds_read_b128 v[28:31], v159
	ds_read_b128 v[32:35], v161
	ds_read_b128 v[36:39], v163
	ds_read_b128 v[40:43], v172
	ds_read_b128 v[44:47], v173
	ds_read_b128 v[48:51], v174
	ds_read_b128 v[52:55], v175
	ds_read_b128 v[56:59], v176
	ds_read_b128 v[60:63], v177
	s_waitcnt lgkmcnt(0)
	s_barrier
	v_max_u32_e32 v212, v0, v1
	v_min_u32_e32 v1, v0, v1
	v_max_u32_e32 v0, v16, v17
	v_min_u32_e32 v17, v16, v17
	v_max_u32_e32 v16, v32, v33
	v_min_u32_e32 v33, v32, v33
	v_max_u32_e32 v32, v48, v49
	v_min_u32_e32 v49, v48, v49
	v_max_u32_e32 v48, v2, v3
	v_min_u32_e32 v3, v2, v3
	v_max_u32_e32 v2, v18, v19
	v_min_u32_e32 v19, v18, v19
	v_max_u32_e32 v18, v34, v35
	v_min_u32_e32 v35, v34, v35
	v_max_u32_e32 v34, v50, v51
	v_min_u32_e32 v51, v50, v51
	v_max_u32_e32 v50, v212, v48
	v_min_u32_e32 v48, v212, v48
	v_max_u32_e32 v212, v0, v2
	v_min_u32_e32 v2, v0, v2
	v_max_u32_e32 v0, v16, v18
	v_min_u32_e32 v18, v16, v18
	v_max_u32_e32 v16, v32, v34
	v_min_u32_e32 v34, v32, v34
	v_max_u32_e32 v32, v1, v3
	v_min_u32_e32 v3, v1, v3
	v_max_u32_e32 v1, v17, v19
	v_min_u32_e32 v19, v17, v19
	v_max_u32_e32 v17, v33, v35
	v_min_u32_e32 v35, v33, v35
	v_max_u32_e32 v33, v49, v51
	v_min_u32_e32 v51, v49, v51
	v_max_u32_e32 v49, v32, v48
	v_min_u32_e32 v48, v32, v48
	v_max_u32_e32 v32, v1, v2
	v_min_u32_e32 v2, v1, v2
	v_max_u32_e32 v1, v17, v18
	v_min_u32_e32 v18, v17, v18
	v_max_u32_e32 v17, v33, v34
	v_min_u32_e32 v34, v33, v34
	v_max_u32_e32 v33, v4, v5
	v_min_u32_e32 v5, v4, v5
	v_max_u32_e32 v4, v20, v21
	v_min_u32_e32 v21, v20, v21
	v_max_u32_e32 v20, v36, v37
	v_min_u32_e32 v37, v36, v37
	v_max_u32_e32 v36, v52, v53
	v_min_u32_e32 v53, v52, v53
	v_max_u32_e32 v52, v6, v7
	v_min_u32_e32 v7, v6, v7
	v_max_u32_e32 v6, v22, v23
	v_min_u32_e32 v23, v22, v23
	v_max_u32_e32 v22, v38, v39
	v_min_u32_e32 v39, v38, v39
	v_max_u32_e32 v38, v54, v55
	v_min_u32_e32 v55, v54, v55
	v_max_u32_e32 v54, v33, v52
	v_min_u32_e32 v52, v33, v52
	v_max_u32_e32 v33, v4, v6
	v_min_u32_e32 v6, v4, v6
	v_max_u32_e32 v4, v20, v22
	v_min_u32_e32 v22, v20, v22
	v_max_u32_e32 v20, v36, v38
	v_min_u32_e32 v38, v36, v38
	v_max_u32_e32 v36, v5, v7
	v_min_u32_e32 v7, v5, v7
	v_max_u32_e32 v5, v21, v23
	v_min_u32_e32 v23, v21, v23
	v_max_u32_e32 v21, v37, v39
	v_min_u32_e32 v39, v37, v39
	v_max_u32_e32 v37, v53, v55
	v_min_u32_e32 v55, v53, v55
	v_max_u32_e32 v53, v36, v52
	v_min_u32_e32 v52, v36, v52
	v_max_u32_e32 v36, v5, v6
	v_min_u32_e32 v6, v5, v6
	v_max_u32_e32 v5, v21, v22
	v_min_u32_e32 v22, v21, v22
	v_max_u32_e32 v21, v37, v38
	v_min_u32_e32 v38, v37, v38
	v_max_u32_e32 v37, v50, v54
	v_min_u32_e32 v54, v50, v54
	v_max_u32_e32 v50, v212, v33
	v_min_u32_e32 v33, v212, v33
	v_max_u32_e32 v212, v0, v4
	v_min_u32_e32 v4, v0, v4
	v_max_u32_e32 v0, v16, v20
	v_min_u32_e32 v20, v16, v20
	v_max_u32_e32 v16, v48, v52
	v_min_u32_e32 v52, v48, v52
	v_max_u32_e32 v48, v2, v6
	v_min_u32_e32 v6, v2, v6
	v_max_u32_e32 v2, v18, v22
	v_min_u32_e32 v22, v18, v22
	v_max_u32_e32 v18, v34, v38
	v_min_u32_e32 v38, v34, v38
	v_max_u32_e32 v34, v16, v54
	v_min_u32_e32 v54, v16, v54
	v_max_u32_e32 v16, v48, v33
	v_min_u32_e32 v33, v48, v33
	v_max_u32_e32 v48, v2, v4
	v_min_u32_e32 v4, v2, v4
	v_max_u32_e32 v2, v18, v20
	v_min_u32_e32 v20, v18, v20
	v_max_u32_e32 v18, v49, v53
	v_min_u32_e32 v53, v49, v53
	v_max_u32_e32 v49, v32, v36
	v_min_u32_e32 v36, v32, v36
	v_max_u32_e32 v32, v1, v5
	v_min_u32_e32 v5, v1, v5
	v_max_u32_e32 v1, v17, v21
	v_min_u32_e32 v21, v17, v21
	v_max_u32_e32 v17, v3, v7
	v_min_u32_e32 v7, v3, v7
	v_max_u32_e32 v3, v19, v23
	v_min_u32_e32 v23, v19, v23
	v_max_u32_e32 v19, v35, v39
	v_min_u32_e32 v39, v35, v39
	v_max_u32_e32 v35, v51, v55
	v_min_u32_e32 v55, v51, v55
	v_max_u32_e32 v51, v17, v53
	v_min_u32_e32 v53, v17, v53
	v_max_u32_e32 v17, v3, v36
	v_min_u32_e32 v36, v3, v36
	v_max_u32_e32 v3, v19, v5
	v_min_u32_e32 v5, v19, v5
	v_max_u32_e32 v19, v35, v21
	v_min_u32_e32 v21, v35, v21
	v_max_u32_e32 v35, v18, v34
	v_min_u32_e32 v34, v18, v34
	v_max_u32_e32 v18, v49, v16
	v_min_u32_e32 v16, v49, v16
	v_max_u32_e32 v49, v32, v48
	v_min_u32_e32 v48, v32, v48
	v_max_u32_e32 v32, v1, v2
	v_min_u32_e32 v2, v1, v2
	v_max_u32_e32 v1, v51, v54
	v_min_u32_e32 v54, v51, v54
	v_max_u32_e32 v51, v17, v33
	v_min_u32_e32 v33, v17, v33
	v_max_u32_e32 v17, v3, v4
	v_min_u32_e32 v4, v3, v4
	v_max_u32_e32 v3, v19, v20
	v_min_u32_e32 v20, v19, v20
	v_max_u32_e32 v19, v53, v52
	v_min_u32_e32 v52, v53, v52
	v_max_u32_e32 v53, v36, v6
	v_min_u32_e32 v6, v36, v6
	v_max_u32_e32 v36, v5, v22
	v_min_u32_e32 v22, v5, v22
	v_max_u32_e32 v5, v21, v38
	v_min_u32_e32 v38, v21, v38
	v_max_u32_e32 v21, v8, v9
	v_min_u32_e32 v9, v8, v9
	v_max_u32_e32 v8, v24, v25
	v_min_u32_e32 v25, v24, v25
	v_max_u32_e32 v24, v40, v41
	v_min_u32_e32 v41, v40, v41
	v_max_u32_e32 v40, v56, v57
	v_min_u32_e32 v57, v56, v57
	v_max_u32_e32 v56, v10, v11
	v_min_u32_e32 v11, v10, v11
	v_max_u32_e32 v10, v26, v27
	v_min_u32_e32 v27, v26, v27
	v_max_u32_e32 v26, v42, v43
	v_min_u32_e32 v43, v42, v43
	v_max_u32_e32 v42, v58, v59
	v_min_u32_e32 v59, v58, v59
	v_max_u32_e32 v58, v21, v56
	v_min_u32_e32 v56, v21, v56
	v_max_u32_e32 v21, v8, v10
	v_min_u32_e32 v10, v8, v10
	v_max_u32_e32 v8, v24, v26
	v_min_u32_e32 v26, v24, v26
	v_max_u32_e32 v24, v40, v42
	v_min_u32_e32 v42, v40, v42
	v_max_u32_e32 v40, v9, v11
	v_min_u32_e32 v11, v9, v11
	v_max_u32_e32 v9, v25, v27
	v_min_u32_e32 v27, v25, v27
	v_max_u32_e32 v25, v41, v43
	v_min_u32_e32 v43, v41, v43
	v_max_u32_e32 v41, v57, v59
	v_min_u32_e32 v59, v57, v59
	v_max_u32_e32 v57, v40, v56
	v_min_u32_e32 v56, v40, v56
	v_max_u32_e32 v40, v9, v10
	v_min_u32_e32 v10, v9, v10
	v_max_u32_e32 v9, v25, v26
	v_min_u32_e32 v26, v25, v26
	v_max_u32_e32 v25, v41, v42
	v_min_u32_e32 v42, v41, v42
	v_max_u32_e32 v41, v12, v13
	v_min_u32_e32 v13, v12, v13
	v_max_u32_e32 v12, v28, v29
	v_min_u32_e32 v29, v28, v29
	v_max_u32_e32 v28, v44, v45
	v_min_u32_e32 v45, v44, v45
	v_max_u32_e32 v44, v60, v61
	v_min_u32_e32 v61, v60, v61
	v_max_u32_e32 v60, v14, v15
	v_min_u32_e32 v15, v14, v15
	v_max_u32_e32 v14, v30, v31
	v_min_u32_e32 v31, v30, v31
	v_max_u32_e32 v30, v46, v47
	v_min_u32_e32 v47, v46, v47
	v_max_u32_e32 v46, v62, v63
	v_min_u32_e32 v63, v62, v63
	v_max_u32_e32 v62, v41, v60
	v_min_u32_e32 v60, v41, v60
	v_max_u32_e32 v41, v12, v14
	v_min_u32_e32 v14, v12, v14
	v_max_u32_e32 v12, v28, v30
	v_min_u32_e32 v30, v28, v30
	v_max_u32_e32 v28, v44, v46
	v_min_u32_e32 v46, v44, v46
	v_max_u32_e32 v44, v13, v15
	v_min_u32_e32 v15, v13, v15
	v_max_u32_e32 v13, v29, v31
	v_min_u32_e32 v31, v29, v31
	v_max_u32_e32 v29, v45, v47
	v_min_u32_e32 v47, v45, v47
	v_max_u32_e32 v45, v61, v63
	v_min_u32_e32 v63, v61, v63
	v_max_u32_e32 v61, v44, v60
	v_min_u32_e32 v60, v44, v60
	v_max_u32_e32 v44, v13, v14
	v_min_u32_e32 v14, v13, v14
	v_max_u32_e32 v13, v29, v30
	v_min_u32_e32 v30, v29, v30
	v_max_u32_e32 v29, v45, v46
	v_min_u32_e32 v46, v45, v46
	v_max_u32_e32 v45, v58, v62
	v_min_u32_e32 v62, v58, v62
	v_max_u32_e32 v58, v21, v41
	v_min_u32_e32 v41, v21, v41
	v_max_u32_e32 v21, v8, v12
	v_min_u32_e32 v12, v8, v12
	v_max_u32_e32 v8, v24, v28
	v_min_u32_e32 v28, v24, v28
	v_max_u32_e32 v24, v56, v60
	v_min_u32_e32 v60, v56, v60
	v_max_u32_e32 v56, v10, v14
	v_min_u32_e32 v14, v10, v14
	v_max_u32_e32 v10, v26, v30
	v_min_u32_e32 v30, v26, v30
	v_max_u32_e32 v26, v42, v46
	v_min_u32_e32 v46, v42, v46
	v_max_u32_e32 v42, v24, v62
	v_min_u32_e32 v62, v24, v62
	v_max_u32_e32 v24, v56, v41
	v_min_u32_e32 v41, v56, v41
	v_max_u32_e32 v56, v10, v12
	v_min_u32_e32 v12, v10, v12
	v_max_u32_e32 v10, v26, v28
	v_min_u32_e32 v28, v26, v28
	v_max_u32_e32 v26, v57, v61
	v_min_u32_e32 v61, v57, v61
	v_max_u32_e32 v57, v40, v44
	v_min_u32_e32 v44, v40, v44
	v_max_u32_e32 v40, v9, v13
	v_min_u32_e32 v13, v9, v13
	v_max_u32_e32 v9, v25, v29
	v_min_u32_e32 v29, v25, v29
	v_max_u32_e32 v25, v11, v15
	v_min_u32_e32 v15, v11, v15
	v_max_u32_e32 v11, v27, v31
	v_min_u32_e32 v31, v27, v31
	v_max_u32_e32 v27, v43, v47
	v_min_u32_e32 v47, v43, v47
	v_max_u32_e32 v43, v59, v63
	v_min_u32_e32 v63, v59, v63
	v_max_u32_e32 v59, v25, v61
	v_min_u32_e32 v61, v25, v61
	v_max_u32_e32 v25, v11, v44
	v_min_u32_e32 v44, v11, v44
	v_max_u32_e32 v11, v27, v13
	v_min_u32_e32 v13, v27, v13
	v_max_u32_e32 v27, v43, v29
	v_min_u32_e32 v29, v43, v29
	v_max_u32_e32 v43, v26, v42
	v_min_u32_e32 v42, v26, v42
	v_max_u32_e32 v26, v57, v24
	v_min_u32_e32 v24, v57, v24
	v_max_u32_e32 v57, v40, v56
	v_min_u32_e32 v56, v40, v56
	v_max_u32_e32 v40, v9, v10
	v_min_u32_e32 v10, v9, v10
	v_max_u32_e32 v9, v59, v62
	v_min_u32_e32 v62, v59, v62
	v_max_u32_e32 v59, v25, v41
	v_min_u32_e32 v41, v25, v41
	v_max_u32_e32 v25, v11, v12
	v_min_u32_e32 v12, v11, v12
	v_max_u32_e32 v11, v27, v28
	v_min_u32_e32 v28, v27, v28
	v_max_u32_e32 v27, v61, v60
	v_min_u32_e32 v60, v61, v60
	v_max_u32_e32 v61, v44, v14
	v_min_u32_e32 v14, v44, v14
	v_max_u32_e32 v44, v13, v30
	v_min_u32_e32 v30, v13, v30
	v_max_u32_e32 v13, v29, v46
	v_min_u32_e32 v46, v29, v46
	v_max_u32_e32 v29, v37, v45
	v_min_u32_e32 v45, v37, v45
	v_max_u32_e32 v37, v50, v58
	v_min_u32_e32 v58, v50, v58
	v_max_u32_e32 v50, v212, v21
	v_min_u32_e32 v21, v212, v21
	v_max_u32_e32 v212, v0, v8
	v_min_u32_e32 v8, v0, v8
	v_max_u32_e32 v0, v54, v62
	v_min_u32_e32 v62, v54, v62
	v_max_u32_e32 v54, v33, v41
	v_min_u32_e32 v41, v33, v41
	v_max_u32_e32 v33, v4, v12
	v_min_u32_e32 v12, v4, v12
	v_max_u32_e32 v4, v20, v28
	v_min_u32_e32 v28, v20, v28
	v_max_u32_e32 v20, v0, v45
	v_min_u32_e32 v45, v0, v45
	v_max_u32_e32 v0, v54, v58
	v_min_u32_e32 v58, v54, v58
	v_max_u32_e32 v54, v33, v21
	v_min_u32_e32 v21, v33, v21
	v_max_u32_e32 v33, v4, v8
	v_min_u32_e32 v8, v4, v8
	v_max_u32_e32 v4, v34, v42
	v_min_u32_e32 v42, v34, v42
	v_max_u32_e32 v34, v16, v24
	v_min_u32_e32 v24, v16, v24
	v_max_u32_e32 v16, v48, v56
	v_min_u32_e32 v56, v48, v56
	v_max_u32_e32 v48, v2, v10
	v_min_u32_e32 v10, v2, v10
	v_max_u32_e32 v2, v52, v60
	v_min_u32_e32 v60, v52, v60
	v_max_u32_e32 v52, v6, v14
	v_min_u32_e32 v14, v6, v14
	v_max_u32_e32 v6, v22, v30
	v_min_u32_e32 v30, v22, v30
	v_max_u32_e32 v22, v38, v46
	v_min_u32_e32 v46, v38, v46
	v_max_u32_e32 v38, v2, v42
	v_min_u32_e32 v42, v2, v42
	v_max_u32_e32 v2, v52, v24
	v_min_u32_e32 v24, v52, v24
	v_max_u32_e32 v52, v6, v56
	v_min_u32_e32 v56, v6, v56
	v_max_u32_e32 v6, v22, v10
	v_min_u32_e32 v10, v22, v10
	v_max_u32_e32 v22, v4, v20
	v_min_u32_e32 v20, v4, v20
	v_max_u32_e32 v4, v34, v0
	v_min_u32_e32 v0, v34, v0
	v_max_u32_e32 v34, v16, v54
	v_min_u32_e32 v54, v16, v54
	v_max_u32_e32 v16, v48, v33
	v_min_u32_e32 v33, v48, v33
	v_max_u32_e32 v48, v38, v45
	v_min_u32_e32 v45, v38, v45
	v_max_u32_e32 v38, v2, v58
	v_min_u32_e32 v58, v2, v58
	v_max_u32_e32 v2, v52, v21
	v_min_u32_e32 v21, v52, v21
	v_max_u32_e32 v52, v6, v8
	v_min_u32_e32 v8, v6, v8
	v_max_u32_e32 v6, v42, v62
	v_min_u32_e32 v62, v42, v62
	v_max_u32_e32 v42, v24, v41
	v_min_u32_e32 v41, v24, v41
	v_max_u32_e32 v24, v56, v12
	v_min_u32_e32 v12, v56, v12
	v_max_u32_e32 v56, v10, v28
	v_min_u32_e32 v28, v10, v28
	v_max_u32_e32 v10, v35, v43
	v_min_u32_e32 v43, v35, v43
	v_max_u32_e32 v35, v18, v26
	v_min_u32_e32 v26, v18, v26
	v_max_u32_e32 v18, v49, v57
	v_min_u32_e32 v57, v49, v57
	v_max_u32_e32 v49, v32, v40
	v_min_u32_e32 v40, v32, v40
	v_max_u32_e32 v32, v19, v27
	v_min_u32_e32 v27, v19, v27
	v_max_u32_e32 v19, v53, v61
	v_min_u32_e32 v61, v53, v61
	v_max_u32_e32 v53, v36, v44
	v_min_u32_e32 v44, v36, v44
	v_max_u32_e32 v36, v5, v13
	v_min_u32_e32 v13, v5, v13
	v_max_u32_e32 v5, v32, v43
	v_min_u32_e32 v43, v32, v43
	v_max_u32_e32 v32, v19, v26
	v_min_u32_e32 v26, v19, v26
	v_max_u32_e32 v19, v53, v57
	v_min_u32_e32 v57, v53, v57
	v_max_u32_e32 v53, v36, v40
	v_min_u32_e32 v40, v36, v40
	v_max_u32_e32 v36, v1, v9
	v_min_u32_e32 v9, v1, v9
	v_max_u32_e32 v1, v51, v59
	v_min_u32_e32 v59, v51, v59
	v_max_u32_e32 v51, v17, v25
	v_min_u32_e32 v25, v17, v25
	v_max_u32_e32 v17, v3, v11
	v_min_u32_e32 v11, v3, v11
	v_max_u32_e32 v3, v7, v15
	v_min_u32_e32 v15, v7, v15
	v_max_u32_e32 v7, v23, v31
	v_min_u32_e32 v31, v23, v31
	v_max_u32_e32 v23, v39, v47
	v_min_u32_e32 v47, v39, v47
	v_max_u32_e32 v39, v55, v63
	v_min_u32_e32 v63, v55, v63
	v_max_u32_e32 v55, v3, v9
	v_min_u32_e32 v9, v3, v9
	v_max_u32_e32 v3, v7, v59
	v_min_u32_e32 v59, v7, v59
	v_max_u32_e32 v7, v23, v25
	v_min_u32_e32 v25, v23, v25
	v_max_u32_e32 v23, v39, v11
	v_min_u32_e32 v11, v39, v11
	v_max_u32_e32 v39, v36, v5
	v_min_u32_e32 v5, v36, v5
	v_max_u32_e32 v36, v1, v32
	v_min_u32_e32 v32, v1, v32
	v_max_u32_e32 v1, v51, v19
	v_min_u32_e32 v19, v51, v19
	v_max_u32_e32 v51, v17, v53
	v_min_u32_e32 v53, v17, v53
	v_max_u32_e32 v17, v55, v43
	v_min_u32_e32 v43, v55, v43
	v_max_u32_e32 v55, v3, v26
	v_min_u32_e32 v26, v3, v26
	v_max_u32_e32 v3, v7, v57
	v_min_u32_e32 v57, v7, v57
	v_max_u32_e32 v7, v23, v40
	v_min_u32_e32 v40, v23, v40
	v_max_u32_e32 v23, v9, v27
	v_min_u32_e32 v27, v9, v27
	v_max_u32_e32 v9, v59, v61
	v_min_u32_e32 v61, v59, v61
	v_max_u32_e32 v59, v25, v44
	v_min_u32_e32 v44, v25, v44
	v_max_u32_e32 v25, v11, v13
	v_min_u32_e32 v13, v11, v13
	v_max_u32_e32 v11, v10, v22
	v_min_u32_e32 v22, v10, v22
	v_max_u32_e32 v10, v35, v4
	v_min_u32_e32 v4, v35, v4
	v_max_u32_e32 v35, v18, v34
	v_min_u32_e32 v34, v18, v34
	v_max_u32_e32 v18, v49, v16
	v_min_u32_e32 v16, v49, v16
	v_max_u32_e32 v49, v39, v20
	v_min_u32_e32 v20, v39, v20
	v_max_u32_e32 v39, v36, v0
	v_min_u32_e32 v0, v36, v0
	v_max_u32_e32 v36, v1, v54
	v_min_u32_e32 v54, v1, v54
	v_max_u32_e32 v1, v51, v33
	v_min_u32_e32 v33, v51, v33
	v_max_u32_e32 v51, v5, v48
	v_min_u32_e32 v48, v5, v48
	v_max_u32_e32 v5, v32, v38
	v_min_u32_e32 v38, v32, v38
	v_max_u32_e32 v32, v19, v2
	v_min_u32_e32 v2, v19, v2
	v_max_u32_e32 v19, v53, v52
	v_min_u32_e32 v52, v53, v52
	v_max_u32_e32 v53, v17, v45
	v_min_u32_e32 v45, v17, v45
	v_max_u32_e32 v17, v55, v58
	v_min_u32_e32 v58, v55, v58
	v_max_u32_e32 v55, v3, v21
	v_min_u32_e32 v21, v3, v21
	v_max_u32_e32 v3, v7, v8
	v_min_u32_e32 v8, v7, v8
	v_max_u32_e32 v7, v43, v6
	v_min_u32_e32 v6, v43, v6
	v_max_u32_e32 v43, v26, v42
	v_min_u32_e32 v42, v26, v42
	v_max_u32_e32 v26, v57, v24
	v_min_u32_e32 v24, v57, v24
	v_max_u32_e32 v57, v40, v56
	v_min_u32_e32 v56, v40, v56
	v_max_u32_e32 v40, v23, v62
	v_min_u32_e32 v62, v23, v62
	v_max_u32_e32 v23, v9, v41
	v_min_u32_e32 v41, v9, v41
	v_max_u32_e32 v9, v59, v12
	v_min_u32_e32 v12, v59, v12
	v_max_u32_e32 v59, v25, v28
	v_min_u32_e32 v28, v25, v28
	v_max_u32_e32 v25, v27, v60
	v_min_u32_e32 v60, v27, v60
	v_max_u32_e32 v27, v61, v14
	v_min_u32_e32 v14, v61, v14
	v_max_u32_e32 v61, v44, v30
	v_min_u32_e32 v30, v44, v30
	v_max_u32_e32 v44, v13, v46
	v_min_u32_e32 v46, v13, v46
	v_max_u32_e32 v29, v29, v31
	v_max_u32_e32 v11, v11, v14
	v_max_u32_e32 v22, v22, v27
	v_max_u32_e32 v49, v49, v41
	v_max_u32_e32 v20, v20, v23
	v_max_u32_e32 v51, v51, v42
	v_max_u32_e32 v48, v48, v43
	v_max_u32_e32 v53, v53, v58
	v_max_u32_e32 v45, v45, v17
	v_max_u32_e32 v7, v7, v38
	v_max_u32_e32 v6, v6, v5
	v_max_u32_e32 v40, v40, v0
	v_max_u32_e32 v62, v62, v39
	v_max_u32_e32 v25, v25, v4
	v_max_u32_e32 v60, v60, v10
	v_max_u32_e32 v15, v15, v37
	v_max_u32_e32 v13, v29, v45
	v_min_u32_e32 v45, v29, v45
	v_max_u32_e32 v29, v11, v7
	v_min_u32_e32 v7, v11, v7
	v_max_u32_e32 v11, v22, v6
	v_min_u32_e32 v6, v22, v6
	v_max_u32_e32 v22, v49, v40
	v_min_u32_e32 v40, v49, v40
	v_max_u32_e32 v49, v20, v62
	v_min_u32_e32 v62, v20, v62
	v_max_u32_e32 v20, v51, v25
	v_min_u32_e32 v25, v51, v25
	v_max_u32_e32 v51, v48, v60
	v_min_u32_e32 v60, v48, v60
	v_max_u32_e32 v48, v53, v15
	v_min_u32_e32 v15, v53, v15
	v_max_u32_e32 v53, v13, v49
	v_min_u32_e32 v49, v13, v49
	v_max_u32_e32 v13, v29, v20
	v_min_u32_e32 v20, v29, v20
	v_max_u32_e32 v29, v11, v51
	v_min_u32_e32 v51, v11, v51
	v_max_u32_e32 v11, v22, v48
	v_min_u32_e32 v48, v22, v48
	v_max_u32_e32 v22, v45, v62
	v_min_u32_e32 v62, v45, v62
	v_max_u32_e32 v45, v7, v25
	v_min_u32_e32 v25, v7, v25
	v_max_u32_e32 v7, v6, v60
	v_min_u32_e32 v60, v6, v60
	v_max_u32_e32 v6, v40, v15
	v_min_u32_e32 v15, v40, v15
	v_max_u32_e32 v40, v53, v29
	v_min_u32_e32 v29, v53, v29
	v_max_u32_e32 v53, v13, v11
	v_min_u32_e32 v11, v13, v11
	v_max_u32_e32 v13, v49, v51
	v_min_u32_e32 v51, v49, v51
	v_max_u32_e32 v49, v20, v48
	v_min_u32_e32 v48, v20, v48
	v_max_u32_e32 v20, v22, v7
	v_min_u32_e32 v7, v22, v7
	v_max_u32_e32 v22, v45, v6
	v_min_u32_e32 v6, v45, v6
	v_max_u32_e32 v45, v62, v60
	v_min_u32_e32 v60, v62, v60
	v_max_u32_e32 v62, v25, v15
	v_min_u32_e32 v15, v25, v15
	v_max_u32_e32 v25, v40, v53
	v_min_u32_e32 v53, v40, v53
	v_max_u32_e32 v40, v29, v11
	v_min_u32_e32 v11, v29, v11
	v_max_u32_e32 v29, v13, v49
	v_min_u32_e32 v49, v13, v49
	v_max_u32_e32 v13, v51, v48
	v_min_u32_e32 v48, v51, v48
	v_max_u32_e32 v51, v20, v22
	v_min_u32_e32 v22, v20, v22
	v_max_u32_e32 v20, v7, v6
	v_min_u32_e32 v6, v7, v6
	v_max_u32_e32 v7, v45, v62
	v_min_u32_e32 v62, v45, v62
	v_max_u32_e32 v45, v60, v15
	v_min_u32_e32 v15, v60, v15
	v_max_u32_e32 v50, v50, v63
	v_max_u32_e32 v35, v35, v46
	v_max_u32_e32 v34, v34, v44
	v_max_u32_e32 v36, v36, v28
	v_max_u32_e32 v54, v54, v59
	v_max_u32_e32 v32, v32, v56
	v_max_u32_e32 v2, v2, v57
	v_max_u32_e32 v55, v55, v8
	v_max_u32_e32 v21, v21, v3
	v_max_u32_e32 v26, v26, v52
	v_max_u32_e32 v24, v24, v19
	v_max_u32_e32 v9, v9, v33
	v_max_u32_e32 v12, v12, v1
	v_max_u32_e32 v61, v61, v16
	v_max_u32_e32 v30, v30, v18
	v_max_u32_e32 v47, v47, v212
	v_max_u32_e32 v60, v50, v21
	v_min_u32_e32 v21, v50, v21
	v_max_u32_e32 v50, v35, v26
	v_min_u32_e32 v26, v35, v26
	v_max_u32_e32 v35, v34, v24
	v_min_u32_e32 v24, v34, v24
	v_max_u32_e32 v34, v36, v9
	v_min_u32_e32 v9, v36, v9
	v_max_u32_e32 v36, v54, v12
	v_min_u32_e32 v12, v54, v12
	v_max_u32_e32 v54, v32, v61
	v_min_u32_e32 v61, v32, v61
	v_max_u32_e32 v32, v2, v30
	v_min_u32_e32 v30, v2, v30
	v_max_u32_e32 v2, v55, v47
	v_min_u32_e32 v47, v55, v47
	v_max_u32_e32 v55, v60, v36
	v_min_u32_e32 v36, v60, v36
	v_max_u32_e32 v60, v50, v54
	v_min_u32_e32 v54, v50, v54
	v_max_u32_e32 v50, v35, v32
	v_min_u32_e32 v32, v35, v32
	v_max_u32_e32 v35, v34, v2
	v_min_u32_e32 v2, v34, v2
	v_max_u32_e32 v34, v21, v12
	v_min_u32_e32 v12, v21, v12
	v_max_u32_e32 v21, v26, v61
	v_min_u32_e32 v61, v26, v61
	v_max_u32_e32 v26, v24, v30
	v_min_u32_e32 v30, v24, v30
	v_max_u32_e32 v24, v9, v47
	v_min_u32_e32 v47, v9, v47
	v_max_u32_e32 v9, v55, v50
	v_min_u32_e32 v50, v55, v50
	v_max_u32_e32 v55, v60, v35
	v_min_u32_e32 v35, v60, v35
	v_max_u32_e32 v60, v36, v32
	v_min_u32_e32 v32, v36, v32
	v_max_u32_e32 v36, v54, v2
	v_min_u32_e32 v2, v54, v2
	v_max_u32_e32 v54, v34, v26
	v_min_u32_e32 v26, v34, v26
	v_max_u32_e32 v34, v21, v24
	v_min_u32_e32 v24, v21, v24
	v_max_u32_e32 v21, v12, v30
	v_min_u32_e32 v30, v12, v30
	v_max_u32_e32 v12, v61, v47
	v_min_u32_e32 v47, v61, v47
	v_max_u32_e32 v61, v9, v55
	v_min_u32_e32 v55, v9, v55
	v_max_u32_e32 v9, v50, v35
	v_min_u32_e32 v35, v50, v35
	v_max_u32_e32 v50, v60, v36
	v_min_u32_e32 v36, v60, v36
	v_max_u32_e32 v60, v32, v2
	v_min_u32_e32 v2, v32, v2
	v_max_u32_e32 v32, v54, v34
	v_min_u32_e32 v34, v54, v34
	v_max_u32_e32 v54, v26, v24
	v_min_u32_e32 v24, v26, v24
	v_max_u32_e32 v26, v21, v12
	v_min_u32_e32 v12, v21, v12
	v_max_u32_e32 v21, v30, v47
	v_min_u32_e32 v47, v30, v47
	v_max_u32_e32 v25, v25, v47
	v_max_u32_e32 v53, v53, v21
	v_max_u32_e32 v40, v40, v12
	v_max_u32_e32 v11, v11, v26
	v_max_u32_e32 v29, v29, v24
	v_max_u32_e32 v49, v49, v54
	v_max_u32_e32 v13, v13, v34
	v_max_u32_e32 v48, v48, v32
	v_max_u32_e32 v51, v51, v2
	v_max_u32_e32 v22, v22, v60
	v_max_u32_e32 v20, v20, v36
	v_max_u32_e32 v6, v6, v50
	v_max_u32_e32 v7, v7, v35
	v_max_u32_e32 v62, v62, v9
	v_max_u32_e32 v45, v45, v55
	v_max_u32_e32 v15, v15, v61
	v_max_u32_e32 v30, v25, v51
	v_min_u32_e32 v51, v25, v51
	v_max_u32_e32 v25, v53, v22
	v_min_u32_e32 v22, v53, v22
	v_max_u32_e32 v53, v40, v20
	v_min_u32_e32 v20, v40, v20
	v_max_u32_e32 v40, v11, v6
	v_min_u32_e32 v6, v11, v6
	v_max_u32_e32 v11, v29, v7
	v_min_u32_e32 v7, v29, v7
	v_max_u32_e32 v29, v49, v62
	v_min_u32_e32 v62, v49, v62
	v_max_u32_e32 v49, v13, v45
	v_min_u32_e32 v45, v13, v45
	v_max_u32_e32 v13, v48, v15
	v_min_u32_e32 v15, v48, v15
	v_max_u32_e32 v48, v30, v11
	v_min_u32_e32 v11, v30, v11
	v_max_u32_e32 v30, v25, v29
	v_min_u32_e32 v29, v25, v29
	v_max_u32_e32 v25, v53, v49
	v_min_u32_e32 v49, v53, v49
	v_max_u32_e32 v53, v40, v13
	v_min_u32_e32 v13, v40, v13
	v_max_u32_e32 v40, v51, v7
	v_min_u32_e32 v7, v51, v7
	v_max_u32_e32 v51, v22, v62
	v_min_u32_e32 v62, v22, v62
	v_max_u32_e32 v22, v20, v45
	v_min_u32_e32 v45, v20, v45
	v_max_u32_e32 v20, v6, v15
	v_min_u32_e32 v15, v6, v15
	v_max_u32_e32 v6, v48, v25
	v_min_u32_e32 v25, v48, v25
	v_max_u32_e32 v48, v30, v53
	v_min_u32_e32 v53, v30, v53
	v_max_u32_e32 v30, v11, v49
	v_min_u32_e32 v49, v11, v49
	v_max_u32_e32 v11, v29, v13
	v_min_u32_e32 v13, v29, v13
	v_max_u32_e32 v29, v40, v22
	v_min_u32_e32 v22, v40, v22
	v_max_u32_e32 v40, v51, v20
	v_min_u32_e32 v20, v51, v20
	v_max_u32_e32 v51, v7, v45
	v_min_u32_e32 v45, v7, v45
	v_max_u32_e32 v7, v62, v15
	v_min_u32_e32 v15, v62, v15
	v_max_u32_e32 v62, v6, v48
	v_min_u32_e32 v48, v6, v48
	v_max_u32_e32 v6, v25, v53
	v_min_u32_e32 v53, v25, v53
	v_max_u32_e32 v25, v30, v11
	v_min_u32_e32 v11, v30, v11
	v_max_u32_e32 v30, v49, v13
	v_min_u32_e32 v13, v49, v13
	v_max_u32_e32 v49, v29, v40
	v_min_u32_e32 v40, v29, v40
	v_max_u32_e32 v29, v22, v20
	v_min_u32_e32 v20, v22, v20
	v_max_u32_e32 v22, v51, v7
	v_min_u32_e32 v7, v51, v7
	v_max_u32_e32 v51, v45, v15
	v_min_u32_e32 v15, v45, v15
	ds_write_b32 v134, v62
	ds_write_b32 v134, v48 offset:1024
	ds_write_b32 v134, v6 offset:2048
	ds_write_b32 v134, v53 offset:3072
	ds_write_b32 v134, v25 offset:4096
	ds_write_b32 v134, v11 offset:5120
	ds_write_b32 v134, v30 offset:6144
	ds_write_b32 v134, v13 offset:7168
	ds_write_b32 v134, v49 offset:8192
	ds_write_b32 v134, v40 offset:9216
	ds_write_b32 v134, v29 offset:10240
	ds_write_b32 v134, v20 offset:11264
	ds_write_b32 v134, v22 offset:12288
	ds_write_b32 v134, v7 offset:13312
	ds_write_b32 v134, v51 offset:14336
	ds_write_b32 v134, v15 offset:15360
	s_waitcnt lgkmcnt(0)
	s_barrier
	s_and_saveexec_b64 s[8:9], s[12:13]
	s_cbranch_execz .LBB0_621
	s_and_b64 s[14:15], s[4:5], exec
	s_cselect_b32 s2, s17, s27
	s_cselect_b32 s14, s18, s28
	v_add_u32_e32 v216, s14, v156
	v_add_u32_e32 v217, s2, v162
	ds_read_b32 v218, v134 offset:512
	ds_read_b32 v219, v134 offset:1536
	ds_read_b32 v220, v134 offset:2560
	ds_read_b32 v221, v134 offset:3584
	ds_read_b32 v222, v134 offset:4608
	ds_read_b32 v223, v134 offset:5632
	ds_read_b32 v224, v134 offset:6656
	ds_read_b32 v225, v134 offset:7680
	ds_read_b32 v226, v134 offset:8704
	ds_read_b32 v227, v134 offset:9728
	ds_read_b32 v228, v134 offset:10752
	ds_read_b32 v229, v134 offset:11776
	ds_read_b32 v230, v134 offset:12800
	ds_read_b32 v231, v134 offset:13824
	ds_read_b32 v232, v134 offset:14848
	ds_read_b32 v233, v134 offset:15872
	s_waitcnt lgkmcnt(0)
	v_max_u32_e32 v62, v62, v233
	v_max_u32_e32 v48, v48, v232
	v_max_u32_e32 v6, v6, v231
	v_max_u32_e32 v53, v53, v230
	v_max_u32_e32 v25, v25, v229
	v_max_u32_e32 v11, v11, v228
	v_max_u32_e32 v30, v30, v227
	v_max_u32_e32 v13, v13, v226
	v_max_u32_e32 v49, v49, v225
	v_max_u32_e32 v40, v40, v224
	v_max_u32_e32 v29, v29, v223
	v_max_u32_e32 v20, v20, v222
	v_max_u32_e32 v22, v22, v221
	v_max_u32_e32 v7, v7, v220
	v_max_u32_e32 v51, v51, v219
	v_max_u32_e32 v15, v15, v218
	v_max_u32_e32 v45, v62, v49
	v_min_u32_e32 v49, v62, v49
	v_max_u32_e32 v62, v48, v40
	v_min_u32_e32 v40, v48, v40
	v_max_u32_e32 v48, v6, v29
	v_min_u32_e32 v29, v6, v29
	v_max_u32_e32 v6, v53, v20
	v_min_u32_e32 v20, v53, v20
	v_max_u32_e32 v53, v25, v22
	v_min_u32_e32 v22, v25, v22
	v_max_u32_e32 v25, v11, v7
	v_min_u32_e32 v7, v11, v7
	v_max_u32_e32 v11, v30, v51
	v_min_u32_e32 v51, v30, v51
	v_max_u32_e32 v30, v13, v15
	v_min_u32_e32 v15, v13, v15
	v_max_u32_e32 v13, v45, v53
	v_min_u32_e32 v53, v45, v53
	v_max_u32_e32 v45, v62, v25
	v_min_u32_e32 v25, v62, v25
	v_max_u32_e32 v62, v48, v11
	v_min_u32_e32 v11, v48, v11
	v_max_u32_e32 v48, v6, v30
	v_min_u32_e32 v30, v6, v30
	v_max_u32_e32 v6, v49, v22
	v_min_u32_e32 v22, v49, v22
	v_max_u32_e32 v49, v40, v7
	v_min_u32_e32 v7, v40, v7
	v_max_u32_e32 v40, v29, v51
	v_min_u32_e32 v51, v29, v51
	v_max_u32_e32 v29, v20, v15
	v_min_u32_e32 v15, v20, v15
	v_max_u32_e32 v20, v13, v62
	v_min_u32_e32 v62, v13, v62
	v_max_u32_e32 v13, v45, v48
	v_min_u32_e32 v48, v45, v48
	v_max_u32_e32 v45, v53, v11
	v_min_u32_e32 v11, v53, v11
	v_max_u32_e32 v53, v25, v30
	v_min_u32_e32 v30, v25, v30
	v_max_u32_e32 v25, v6, v40
	v_min_u32_e32 v40, v6, v40
	v_max_u32_e32 v6, v49, v29
	v_min_u32_e32 v29, v49, v29
	v_max_u32_e32 v49, v22, v51
	v_min_u32_e32 v51, v22, v51
	v_max_u32_e32 v22, v7, v15
	v_min_u32_e32 v15, v7, v15
	v_max_u32_e32 v7, v20, v13
	v_min_u32_e32 v13, v20, v13
	v_max_u32_e32 v20, v62, v48
	v_min_u32_e32 v48, v62, v48
	v_max_u32_e32 v62, v45, v53
	v_min_u32_e32 v53, v45, v53
	v_max_u32_e32 v45, v11, v30
	v_min_u32_e32 v30, v11, v30
	v_max_u32_e32 v11, v25, v6
	v_min_u32_e32 v6, v25, v6
	v_max_u32_e32 v25, v40, v29
	v_min_u32_e32 v29, v40, v29
	v_max_u32_e32 v40, v49, v22
	v_min_u32_e32 v22, v49, v22
	v_max_u32_e32 v49, v51, v15
	v_min_u32_e32 v15, v51, v15
	v_cmp_gt_i32_e32 vcc, 0, v7
	v_and_b32_e32 v213, 0x7fffff80, v7
	v_not_b32_e32 v214, v7
	v_or_b32_e32 v214, 0x7f, v214
	v_cndmask_b32_e32 v213, v214, v213, vcc
	v_not_b32_e32 v215, v7
	v_and_b32_e32 v215, 0x7f, v215
	ds_write_b32 v217, v213
	ds_write_b8 v216, v215
	v_cmp_gt_i32_e32 vcc, 0, v13
	v_and_b32_e32 v214, 0x7fffff80, v13
	v_not_b32_e32 v215, v13
	v_or_b32_e32 v215, 0x7f, v215
	v_cndmask_b32_e32 v214, v215, v214, vcc
	v_not_b32_e32 v213, v13
	v_and_b32_e32 v213, 0x7f, v213
	ds_write_b32 v217, v214 offset:512
	ds_write_b8 v216, v213 offset:128
	v_cmp_gt_i32_e32 vcc, 0, v20
	v_and_b32_e32 v215, 0x7fffff80, v20
	v_not_b32_e32 v213, v20
	v_or_b32_e32 v213, 0x7f, v213
	v_cndmask_b32_e32 v215, v213, v215, vcc
	v_not_b32_e32 v214, v20
	v_and_b32_e32 v214, 0x7f, v214
	ds_write_b32 v217, v215 offset:1024
	ds_write_b8 v216, v214 offset:256
	v_cmp_gt_i32_e32 vcc, 0, v48
	v_and_b32_e32 v213, 0x7fffff80, v48
	v_not_b32_e32 v214, v48
	v_or_b32_e32 v214, 0x7f, v214
	v_cndmask_b32_e32 v213, v214, v213, vcc
	v_not_b32_e32 v215, v48
	v_and_b32_e32 v215, 0x7f, v215
	ds_write_b32 v217, v213 offset:1536
	ds_write_b8 v216, v215 offset:384
	v_cmp_gt_i32_e32 vcc, 0, v62
	v_and_b32_e32 v214, 0x7fffff80, v62
	v_not_b32_e32 v215, v62
	v_or_b32_e32 v215, 0x7f, v215
	v_cndmask_b32_e32 v214, v215, v214, vcc
	v_not_b32_e32 v213, v62
	v_and_b32_e32 v213, 0x7f, v213
	ds_write_b32 v217, v214 offset:2048
	ds_write_b8 v216, v213 offset:512
	v_cmp_gt_i32_e32 vcc, 0, v53
	v_and_b32_e32 v215, 0x7fffff80, v53
	v_not_b32_e32 v213, v53
	v_or_b32_e32 v213, 0x7f, v213
	v_cndmask_b32_e32 v215, v213, v215, vcc
	v_not_b32_e32 v214, v53
	v_and_b32_e32 v214, 0x7f, v214
	ds_write_b32 v217, v215 offset:2560
	ds_write_b8 v216, v214 offset:640
	v_cmp_gt_i32_e32 vcc, 0, v45
	v_and_b32_e32 v213, 0x7fffff80, v45
	v_not_b32_e32 v214, v45
	v_or_b32_e32 v214, 0x7f, v214
	v_cndmask_b32_e32 v213, v214, v213, vcc
	v_not_b32_e32 v215, v45
	v_and_b32_e32 v215, 0x7f, v215
	ds_write_b32 v217, v213 offset:3072
	ds_write_b8 v216, v215 offset:768
	v_cmp_gt_i32_e32 vcc, 0, v30
	v_and_b32_e32 v214, 0x7fffff80, v30
	v_not_b32_e32 v215, v30
	v_or_b32_e32 v215, 0x7f, v215
	v_cndmask_b32_e32 v214, v215, v214, vcc
	v_not_b32_e32 v213, v30
	v_and_b32_e32 v213, 0x7f, v213
	ds_write_b32 v217, v214 offset:3584
	ds_write_b8 v216, v213 offset:896
	v_cmp_gt_i32_e32 vcc, 0, v11
	v_and_b32_e32 v215, 0x7fffff80, v11
	v_not_b32_e32 v213, v11
	v_or_b32_e32 v213, 0x7f, v213
	v_cndmask_b32_e32 v215, v213, v215, vcc
	v_not_b32_e32 v214, v11
	v_and_b32_e32 v214, 0x7f, v214
	ds_write_b32 v217, v215 offset:4096
	ds_write_b8 v216, v214 offset:1024
	v_cmp_gt_i32_e32 vcc, 0, v6
	v_and_b32_e32 v213, 0x7fffff80, v6
	v_not_b32_e32 v214, v6
	v_or_b32_e32 v214, 0x7f, v214
	v_cndmask_b32_e32 v213, v214, v213, vcc
	v_not_b32_e32 v215, v6
	v_and_b32_e32 v215, 0x7f, v215
	ds_write_b32 v217, v213 offset:4608
	ds_write_b8 v216, v215 offset:1152
	v_cmp_gt_i32_e32 vcc, 0, v25
	v_and_b32_e32 v214, 0x7fffff80, v25
	v_not_b32_e32 v215, v25
	v_or_b32_e32 v215, 0x7f, v215
	v_cndmask_b32_e32 v214, v215, v214, vcc
	v_not_b32_e32 v213, v25
	v_and_b32_e32 v213, 0x7f, v213
	ds_write_b32 v217, v214 offset:5120
	ds_write_b8 v216, v213 offset:1280
	v_cmp_gt_i32_e32 vcc, 0, v29
	v_and_b32_e32 v215, 0x7fffff80, v29
	v_not_b32_e32 v213, v29
	v_or_b32_e32 v213, 0x7f, v213
	v_cndmask_b32_e32 v215, v213, v215, vcc
	v_not_b32_e32 v214, v29
	v_and_b32_e32 v214, 0x7f, v214
	ds_write_b32 v217, v215 offset:5632
	ds_write_b8 v216, v214 offset:1408
	v_cmp_gt_i32_e32 vcc, 0, v40
	v_and_b32_e32 v213, 0x7fffff80, v40
	v_not_b32_e32 v214, v40
	v_or_b32_e32 v214, 0x7f, v214
	v_cndmask_b32_e32 v213, v214, v213, vcc
	v_not_b32_e32 v215, v40
	v_and_b32_e32 v215, 0x7f, v215
	ds_write_b32 v217, v213 offset:6144
	ds_write_b8 v216, v215 offset:1536
	v_cmp_gt_i32_e32 vcc, 0, v22
	v_and_b32_e32 v214, 0x7fffff80, v22
	v_not_b32_e32 v215, v22
	v_or_b32_e32 v215, 0x7f, v215
	v_cndmask_b32_e32 v214, v215, v214, vcc
	v_not_b32_e32 v213, v22
	v_and_b32_e32 v213, 0x7f, v213
	ds_write_b32 v217, v214 offset:6656
	ds_write_b8 v216, v213 offset:1664
	v_cmp_gt_i32_e32 vcc, 0, v49
	v_and_b32_e32 v215, 0x7fffff80, v49
	v_not_b32_e32 v213, v49
	v_or_b32_e32 v213, 0x7f, v213
	v_cndmask_b32_e32 v215, v213, v215, vcc
	v_not_b32_e32 v214, v49
	v_and_b32_e32 v214, 0x7f, v214
	ds_write_b32 v217, v215 offset:7168
	ds_write_b8 v216, v214 offset:1792
	v_cmp_gt_i32_e32 vcc, 0, v15
	v_and_b32_e32 v213, 0x7fffff80, v15
	v_not_b32_e32 v214, v15
	v_or_b32_e32 v214, 0x7f, v214
	v_cndmask_b32_e32 v213, v214, v213, vcc
	v_not_b32_e32 v215, v15
	v_and_b32_e32 v215, 0x7f, v215
	ds_write_b32 v217, v213 offset:7680
	ds_write_b8 v216, v215 offset:1920
	s_branch .LBB0_621

.LBB0_1084:
	s_or_b32 s8, s0, s57
	s_lshl_b32 s8, s8, 15
	s_add_u32 s8, s66, s8
	s_addc_u32 s9, s67, 0
	s_lshl_b32 s0, s0, 8
	s_or_b32 s0, s0, s58
	v_lshl_add_u64 v[16:17], v[66:67], 0, s[0:1]
	v_lshl_add_u64 v[0:1], s[8:9], 0, v[64:65]
	v_mov_b32_e32 v85, v65
	v_mov_b32_e32 v87, v65
	v_mov_b32_e32 v89, v65
	v_mov_b32_e32 v91, v65
	v_lshl_add_u64 v[32:33], v[16:17], 0, v[92:93]
	v_lshl_add_u64 v[8:9], v[0:1], 0, v[84:85]
	v_lshl_add_u64 v[12:13], v[0:1], 0, v[86:87]
	v_lshl_add_u64 v[2:3], v[0:1], 0, v[88:89]
	v_lshl_add_u64 v[4:5], v[0:1], 0, v[90:91]
	v_lshl_add_u64 v[34:35], v[16:17], 0, v[94:95]
	v_lshl_add_u64 v[36:37], v[16:17], 0, v[96:97]
	global_load_dwordx4 v[0:3], v[2:3], off
	s_nop 0
	global_load_dwordx4 v[4:7], v[4:5], off
	s_nop 0
	global_load_dwordx4 v[8:11], v[8:9], off
	s_nop 0
	global_load_dwordx4 v[12:15], v[12:13], off
	v_lshl_add_u64 v[38:39], v[16:17], 0, v[98:99]
	global_load_dwordx4 v[16:19], v[32:33], off
	global_load_dwordx4 v[20:23], v[34:35], off
	global_load_dwordx4 v[24:27], v[36:37], off
	global_load_dwordx4 v[28:31], v[38:39], off
	v_lshl_add_u64 v[40:41], s[8:9], 0, v[84:85]
	v_lshl_add_u64 v[42:43], s[8:9], 0, v[86:87]
	v_lshl_add_u64 v[44:45], s[8:9], 0, v[88:89]
	v_lshl_add_u64 v[46:47], s[8:9], 0, v[90:91]
	v_lshl_add_u64 v[40:41], v[40:41], 0, v[64:65]
	v_lshl_add_u64 v[42:43], v[42:43], 0, v[64:65]
	v_lshl_add_u64 v[44:45], v[44:45], 0, v[64:65]
	v_lshl_add_u64 v[46:47], v[46:47], 0, v[64:65]
	s_barrier
	s_waitcnt vmcnt(6)
	ds_write_b128 v100, v[4:7] offset:18432
	ds_write_b128 v100, v[0:3] offset:23040
	s_waitcnt vmcnt(4)
	ds_write_b128 v100, v[12:15] offset:27648
	ds_write_b128 v100, v[8:11] offset:32256
	s_waitcnt vmcnt(3)
	ds_write_b128 v100, v[16:19]
	s_waitcnt vmcnt(2)
	ds_write_b128 v100, v[20:23] offset:4608
	s_waitcnt vmcnt(1)
	ds_write_b128 v100, v[24:27] offset:9216
	s_waitcnt vmcnt(0)
	ds_write_b128 v100, v[28:31] offset:13824
	s_waitcnt lgkmcnt(0)
	s_barrier
	global_load_dwordx4 v[134:137], v[32:33], off offset:128
	global_load_dwordx4 v[138:141], v[34:35], off offset:128
	global_load_dwordx4 v[142:145], v[36:37], off offset:128
	global_load_dwordx4 v[146:149], v[38:39], off offset:128
	global_load_dwordx4 v[164:167], v[40:41], off offset:128
	global_load_dwordx4 v[186:189], v[42:43], off offset:128
	global_load_dwordx4 v[190:193], v[44:45], off offset:128
	global_load_dwordx4 v[194:197], v[46:47], off offset:128
	ds_read_b128 v[0:3], v102 offset:18432
	ds_read_b128 v[4:7], v101
	ds_read_b128 v[198:201], v101 offset:32
	ds_read_b128 v[202:205], v102 offset:18464
	ds_read_b128 v[8:11], v102 offset:23040
	ds_read_b128 v[212:215], v102 offset:23072
	s_waitcnt lgkmcnt(4)
	v_mfma_f32_32x32x16_bf16 v[48:63], v[0:3], v[4:7], 0
	s_waitcnt lgkmcnt(1)
	v_mfma_f32_32x32x16_bf16 v[32:47], v[8:11], v[4:7], 0
	ds_read_b128 v[4:7], v101 offset:4608
	ds_read_b128 v[216:219], v101 offset:4640
	s_waitcnt lgkmcnt(1)
	v_mfma_f32_32x32x16_bf16 v[16:31], v[0:3], v[4:7], 0
	v_mfma_f32_32x32x16_bf16 v[0:15], v[8:11], v[4:7], 0
	v_mfma_f32_32x32x16_bf16 v[48:63], v[202:205], v[198:201], v[48:63]
	v_mfma_f32_32x32x16_bf16 v[32:47], v[212:215], v[198:201], v[32:47]
	s_waitcnt lgkmcnt(0)
	v_mfma_f32_32x32x16_bf16 v[16:31], v[202:205], v[216:219], v[16:31]
	v_mfma_f32_32x32x16_bf16 v[0:15], v[212:215], v[216:219], v[0:15]
	ds_read_b128 v[198:201], v102 offset:18496
	ds_read_b128 v[202:205], v101 offset:64
	ds_read_b128 v[212:215], v101 offset:96
	ds_read_b128 v[216:219], v102 offset:18528
	ds_read_b128 v[220:223], v102 offset:23104
	ds_read_b128 v[224:227], v102 offset:23136
	s_waitcnt lgkmcnt(4)
	v_mfma_f32_32x32x16_bf16 v[48:63], v[198:201], v[202:205], v[48:63]
	s_waitcnt lgkmcnt(1)
	v_mfma_f32_32x32x16_bf16 v[32:47], v[220:223], v[202:205], v[32:47]
	ds_read_b128 v[202:205], v101 offset:4672
	ds_read_b128 v[228:231], v101 offset:4704
	s_waitcnt lgkmcnt(0)
	s_barrier
	s_waitcnt vmcnt(7)
	ds_write_b128 v100, v[134:137]
	s_waitcnt vmcnt(0)
	ds_write_b128 v100, v[194:197] offset:18432
	ds_write_b128 v100, v[138:141] offset:4608
	ds_write_b128 v100, v[190:193] offset:23040
	ds_write_b128 v100, v[142:145] offset:9216
	ds_write_b128 v100, v[186:189] offset:27648
	ds_write_b128 v100, v[146:149] offset:13824
	ds_write_b128 v100, v[164:167] offset:32256
	s_waitcnt lgkmcnt(0)
	v_mfma_f32_32x32x16_bf16 v[16:31], v[198:201], v[202:205], v[16:31]
	s_barrier
	v_mfma_f32_32x32x16_bf16 v[0:15], v[220:223], v[202:205], v[0:15]
	v_mfma_f32_32x32x16_bf16 v[48:63], v[216:219], v[212:215], v[48:63]
	v_mfma_f32_32x32x16_bf16 v[32:47], v[224:227], v[212:215], v[32:47]
	v_mfma_f32_32x32x16_bf16 v[16:31], v[216:219], v[228:231], v[16:31]
	v_mfma_f32_32x32x16_bf16 v[0:15], v[224:227], v[228:231], v[0:15]
	ds_read_b128 v[134:137], v102 offset:18432
	ds_read_b128 v[138:141], v101
	ds_read_b128 v[142:145], v101 offset:32
	ds_read_b128 v[146:149], v102 offset:18464
	ds_read_b128 v[164:167], v102 offset:23040
	ds_read_b128 v[186:189], v102 offset:23072
	s_waitcnt lgkmcnt(4)
	v_mfma_f32_32x32x16_bf16 v[48:63], v[134:137], v[138:141], v[48:63]
	s_waitcnt lgkmcnt(2)
	v_mfma_f32_32x32x16_bf16 v[48:63], v[146:149], v[142:145], v[48:63]
	s_waitcnt lgkmcnt(1)
	v_mfma_f32_32x32x16_bf16 v[32:47], v[164:167], v[138:141], v[32:47]
	ds_read_b128 v[138:141], v102 offset:18496
	ds_read_b128 v[190:193], v101 offset:64
	ds_read_b128 v[194:197], v101 offset:4608
	ds_read_b128 v[198:201], v101 offset:4640
	ds_read_b128 v[202:205], v101 offset:96
	ds_read_b128 v[212:215], v102 offset:18528
	ds_read_b128 v[216:219], v101 offset:4672
	ds_read_b128 v[220:223], v101 offset:4704
	ds_read_b128 v[224:227], v102 offset:23104
	ds_read_b128 v[228:231], v102 offset:23136
	s_waitcnt lgkmcnt(0)
	s_barrier
	v_mfma_f32_32x32x16_bf16 v[48:63], v[138:141], v[190:193], v[48:63]
	v_mfma_f32_32x32x16_bf16 v[48:63], v[212:215], v[202:205], v[48:63]
	v_mfma_f32_32x32x16_bf16 v[32:47], v[186:189], v[142:145], v[32:47]
	s_nop 10
	v_not_b32_e32 v85, v48
	v_or_b32_e32 v87, 0x80000000, v48
	v_and_b32_e32 v151, 0x7fffffff, v50
	v_and_b32_e32 v150, 0x7fffffff, v49
	v_cmp_gt_i32_e32 vcc, 0, v48
	v_xor_b32_e32 v89, -1, v50
	v_pk_add_f32 v[150:151], v[150:151], 0 neg_lo:[1,1] neg_hi:[1,1]
	v_cndmask_b32_e32 v48, v87, v85, vcc
	v_cmp_gt_i32_e32 vcc, 0, v50
	v_xor_b32_e32 v91, -1, v49
	v_not_b32_e32 v85, v51
	v_cndmask_b32_e32 v50, v151, v89, vcc
	v_cmp_gt_i32_e32 vcc, 0, v49
	v_or_b32_e32 v87, 0x80000000, v51
	v_and_b32_e32 v50, 0xffffff80, v50
	v_cndmask_b32_e32 v49, v150, v91, vcc
	v_cmp_gt_i32_e32 vcc, 0, v51
	v_and_b32_e32 v49, 0xffffff80, v49
	v_and_b32_e32 v48, 0xffffff80, v48
	v_cndmask_b32_e32 v51, v87, v85, vcc
	v_and_b32_e32 v51, 0xffffff80, v51
	v_sub_u32_e32 v49, v49, v68
	v_sub_u32_e32 v50, v50, v69
	v_sub_u32_e32 v51, v51, v68
	v_bitop3_b32 v48, v48, s25, v68 bitop3:0x36
	v_add_u32_e32 v50, 0x7d, v50
	v_add_u32_e32 v49, 0x7e, v49
	v_add_u32_e32 v51, 0x7c, v51
	ds_write_b128 v108, v[48:51]
	v_not_b32_e32 v48, v52
	v_or_b32_e32 v49, 0x80000000, v52
	v_cmp_gt_i32_e32 vcc, 0, v52
	v_and_b32_e32 v51, 0x7fffffff, v54
	v_and_b32_e32 v50, 0x7fffffff, v53
	v_cndmask_b32_e32 v48, v49, v48, vcc
	v_xor_b32_e32 v49, -1, v54
	v_pk_add_f32 v[50:51], v[50:51], 0 neg_lo:[1,1] neg_hi:[1,1]
	v_cmp_gt_i32_e32 vcc, 0, v54
	v_xor_b32_e32 v52, -1, v53
	v_and_b32_e32 v48, 0xffffff80, v48
	v_cndmask_b32_e32 v49, v51, v49, vcc
	v_cmp_gt_i32_e32 vcc, 0, v53
	v_and_b32_e32 v49, 0xffffff80, v49
	v_sub_u32_e32 v49, v49, v71
	v_cndmask_b32_e32 v50, v50, v52, vcc
	v_and_b32_e32 v50, 0xffffff80, v50
	v_sub_u32_e32 v51, v50, v70
	v_add_u32_e32 v50, 0x7d, v49
	v_add_u32_e32 v49, 0x7e, v51
	v_not_b32_e32 v51, v55
	v_or_b32_e32 v52, 0x80000000, v55
	v_cmp_gt_i32_e32 vcc, 0, v55
	v_bitop3_b32 v48, v48, s27, v68 bitop3:0x36
	v_mfma_f32_32x32x16_bf16 v[32:47], v[224:227], v[190:193], v[32:47]
	v_cndmask_b32_e32 v51, v52, v51, vcc
	v_and_b32_e32 v51, 0xffffff80, v51
	v_sub_u32_e32 v51, v51, v70
	v_add_u32_e32 v51, 0x7c, v51
	ds_write_b128 v109, v[48:51]
	v_not_b32_e32 v48, v56
	v_or_b32_e32 v49, 0x80000000, v56
	v_cmp_gt_i32_e32 vcc, 0, v56
	v_and_b32_e32 v51, 0x7fffffff, v58
	v_and_b32_e32 v50, 0x7fffffff, v57
	v_cndmask_b32_e32 v48, v49, v48, vcc
	v_xor_b32_e32 v49, -1, v58
	v_pk_add_f32 v[50:51], v[50:51], 0 neg_lo:[1,1] neg_hi:[1,1]
	v_cmp_gt_i32_e32 vcc, 0, v58
	v_xor_b32_e32 v52, -1, v57
	v_and_b32_e32 v48, 0xffffff80, v48
	v_cndmask_b32_e32 v49, v51, v49, vcc
	v_cmp_gt_i32_e32 vcc, 0, v57
	v_and_b32_e32 v49, 0xffffff80, v49
	v_sub_u32_e32 v49, v49, v73
	v_cndmask_b32_e32 v50, v50, v52, vcc
	v_and_b32_e32 v50, 0xffffff80, v50
	v_sub_u32_e32 v51, v50, v72
	v_add_u32_e32 v50, 0x7d, v49
	v_add_u32_e32 v49, 0x7e, v51
	v_not_b32_e32 v51, v59
	v_or_b32_e32 v52, 0x80000000, v59
	v_cmp_gt_i32_e32 vcc, 0, v59
	v_bitop3_b32 v48, v48, s28, v68 bitop3:0x36
	v_mfma_f32_32x32x16_bf16 v[32:47], v[228:231], v[202:205], v[32:47]
	v_cndmask_b32_e32 v51, v52, v51, vcc
	v_and_b32_e32 v51, 0xffffff80, v51
	v_sub_u32_e32 v51, v51, v72
	v_add_u32_e32 v51, 0x7c, v51
	ds_write_b128 v110, v[48:51]
	v_not_b32_e32 v48, v60
	v_or_b32_e32 v49, 0x80000000, v60
	v_cmp_gt_i32_e32 vcc, 0, v60
	v_and_b32_e32 v51, 0x7fffffff, v62
	v_and_b32_e32 v50, 0x7fffffff, v61
	v_cndmask_b32_e32 v48, v49, v48, vcc
	v_xor_b32_e32 v49, -1, v62
	v_pk_add_f32 v[50:51], v[50:51], 0 neg_lo:[1,1] neg_hi:[1,1]
	v_cmp_gt_i32_e32 vcc, 0, v62
	v_xor_b32_e32 v52, -1, v61
	v_and_b32_e32 v48, 0xffffff80, v48
	v_cndmask_b32_e32 v49, v51, v49, vcc
	v_cmp_gt_i32_e32 vcc, 0, v61
	v_and_b32_e32 v49, 0xffffff80, v49
	v_sub_u32_e32 v49, v49, v75
	v_cndmask_b32_e32 v50, v50, v52, vcc
	v_and_b32_e32 v50, 0xffffff80, v50
	v_sub_u32_e32 v51, v50, v74
	v_add_u32_e32 v50, 0x7d, v49
	v_add_u32_e32 v49, 0x7e, v51
	v_not_b32_e32 v51, v63
	v_or_b32_e32 v52, 0x80000000, v63
	v_cmp_gt_i32_e32 vcc, 0, v63
	v_bitop3_b32 v48, v48, s29, v68 bitop3:0x36
	v_mfma_f32_32x32x16_bf16 v[16:31], v[134:137], v[194:197], v[16:31]
	v_cndmask_b32_e32 v51, v52, v51, vcc
	v_and_b32_e32 v51, 0xffffff80, v51
	v_sub_u32_e32 v51, v51, v74
	v_add_u32_e32 v51, 0x7c, v51
	ds_write_b128 v111, v[48:51]
	v_not_b32_e32 v48, v32
	v_or_b32_e32 v49, 0x80000000, v32
	v_cmp_gt_i32_e32 vcc, 0, v32
	v_xor_b32_e32 v50, -1, v34
	v_xor_b32_e32 v51, -1, v33
	v_cndmask_b32_e32 v32, v49, v48, vcc
	v_and_b32_e32 v49, 0x7fffffff, v34
	v_and_b32_e32 v48, 0x7fffffff, v33
	v_pk_add_f32 v[48:49], v[48:49], 0 neg_lo:[1,1] neg_hi:[1,1]
	v_cmp_gt_i32_e32 vcc, 0, v34
	v_and_b32_e32 v32, 0xffffff80, v32
	v_bitop3_b32 v32, v32, s22, v68 bitop3:0x36
	v_cndmask_b32_e32 v34, v49, v50, vcc
	v_cmp_gt_i32_e32 vcc, 0, v33
	v_or_b32_e32 v49, 0x80000000, v35
	v_and_b32_e32 v34, 0xffffff80, v34
	v_cndmask_b32_e32 v33, v48, v51, vcc
	v_not_b32_e32 v48, v35
	v_cmp_gt_i32_e32 vcc, 0, v35
	v_and_b32_e32 v33, 0xffffff80, v33
	v_sub_u32_e32 v33, v33, v76
	v_cndmask_b32_e32 v35, v49, v48, vcc
	v_and_b32_e32 v35, 0xffffff80, v35
	v_sub_u32_e32 v34, v34, v77
	v_sub_u32_e32 v35, v35, v76
	v_add_u32_e32 v34, 0x7d, v34
	v_add_u32_e32 v33, 0x7e, v33
	v_add_u32_e32 v35, 0x7c, v35
	ds_write_b128 v112, v[32:35]
	v_not_b32_e32 v32, v36
	v_or_b32_e32 v33, 0x80000000, v36
	v_cmp_gt_i32_e32 vcc, 0, v36
	v_and_b32_e32 v35, 0x7fffffff, v38
	v_and_b32_e32 v34, 0x7fffffff, v37
	v_cndmask_b32_e32 v32, v33, v32, vcc
	v_xor_b32_e32 v33, -1, v38
	v_pk_add_f32 v[34:35], v[34:35], 0 neg_lo:[1,1] neg_hi:[1,1]
	v_cmp_gt_i32_e32 vcc, 0, v38
	v_xor_b32_e32 v36, -1, v37
	v_mfma_f32_32x32x16_bf16 v[16:31], v[146:149], v[198:201], v[16:31]
	v_cndmask_b32_e32 v33, v35, v33, vcc
	v_cmp_gt_i32_e32 vcc, 0, v37
	v_and_b32_e32 v33, 0xffffff80, v33
	v_sub_u32_e32 v33, v33, v79
	v_cndmask_b32_e32 v34, v34, v36, vcc
	v_and_b32_e32 v34, 0xffffff80, v34
	v_sub_u32_e32 v35, v34, v78
	v_add_u32_e32 v34, 0x7d, v33
	v_add_u32_e32 v33, 0x7e, v35
	v_not_b32_e32 v35, v39
	v_or_b32_e32 v36, 0x80000000, v39
	v_cmp_gt_i32_e32 vcc, 0, v39
	v_and_b32_e32 v32, 0xffffff80, v32
	v_bitop3_b32 v32, v32, s35, v68 bitop3:0x36
	v_cndmask_b32_e32 v35, v36, v35, vcc
	v_and_b32_e32 v35, 0xffffff80, v35
	v_sub_u32_e32 v35, v35, v78
	v_add_u32_e32 v35, 0x7c, v35
	ds_write_b128 v113, v[32:35]
	v_not_b32_e32 v32, v40
	v_or_b32_e32 v33, 0x80000000, v40
	v_cmp_gt_i32_e32 vcc, 0, v40
	v_and_b32_e32 v35, 0x7fffffff, v42
	v_and_b32_e32 v34, 0x7fffffff, v41
	v_cndmask_b32_e32 v32, v33, v32, vcc
	v_xor_b32_e32 v33, -1, v42
	v_pk_add_f32 v[34:35], v[34:35], 0 neg_lo:[1,1] neg_hi:[1,1]
	v_cmp_gt_i32_e32 vcc, 0, v42
	v_xor_b32_e32 v36, -1, v41
	v_mfma_f32_32x32x16_bf16 v[16:31], v[138:141], v[216:219], v[16:31]
	v_cndmask_b32_e32 v33, v35, v33, vcc
	v_cmp_gt_i32_e32 vcc, 0, v41
	v_and_b32_e32 v33, 0xffffff80, v33
	v_sub_u32_e32 v33, v33, v81
	v_cndmask_b32_e32 v34, v34, v36, vcc
	v_and_b32_e32 v34, 0xffffff80, v34
	v_sub_u32_e32 v35, v34, v80
	v_add_u32_e32 v34, 0x7d, v33
	v_add_u32_e32 v33, 0x7e, v35
	v_not_b32_e32 v35, v43
	v_or_b32_e32 v36, 0x80000000, v43
	v_cmp_gt_i32_e32 vcc, 0, v43
	v_and_b32_e32 v32, 0xffffff80, v32
	v_bitop3_b32 v32, v32, s40, v68 bitop3:0x36
	v_cndmask_b32_e32 v35, v36, v35, vcc
	v_and_b32_e32 v35, 0xffffff80, v35
	v_sub_u32_e32 v35, v35, v80
	v_add_u32_e32 v35, 0x7c, v35
	ds_write_b128 v114, v[32:35]
	v_not_b32_e32 v32, v44
	v_or_b32_e32 v33, 0x80000000, v44
	v_cmp_gt_i32_e32 vcc, 0, v44
	v_and_b32_e32 v35, 0x7fffffff, v46
	v_and_b32_e32 v34, 0x7fffffff, v45
	v_cndmask_b32_e32 v32, v33, v32, vcc
	v_xor_b32_e32 v33, -1, v46
	v_pk_add_f32 v[34:35], v[34:35], 0 neg_lo:[1,1] neg_hi:[1,1]
	v_cmp_gt_i32_e32 vcc, 0, v46
	v_xor_b32_e32 v36, -1, v45
	v_mfma_f32_32x32x16_bf16 v[16:31], v[212:215], v[220:223], v[16:31]
	v_cndmask_b32_e32 v33, v35, v33, vcc
	v_cmp_gt_i32_e32 vcc, 0, v45
	v_and_b32_e32 v33, 0xffffff80, v33
	v_sub_u32_e32 v33, v33, v83
	v_cndmask_b32_e32 v34, v34, v36, vcc
	v_and_b32_e32 v34, 0xffffff80, v34
	v_sub_u32_e32 v35, v34, v82
	v_add_u32_e32 v34, 0x7d, v33
	v_add_u32_e32 v33, 0x7e, v35
	v_not_b32_e32 v35, v47
	v_or_b32_e32 v36, 0x80000000, v47
	v_cmp_gt_i32_e32 vcc, 0, v47
	v_and_b32_e32 v32, 0xffffff80, v32
	v_bitop3_b32 v32, v32, s41, v68 bitop3:0x36
	v_cndmask_b32_e32 v35, v36, v35, vcc
	v_and_b32_e32 v35, 0xffffff80, v35
	v_sub_u32_e32 v35, v35, v82
	v_add_u32_e32 v35, 0x7c, v35
	ds_write_b128 v115, v[32:35]
	v_not_b32_e32 v32, v16
	v_or_b32_e32 v33, 0x80000000, v16
	v_cmp_gt_i32_e32 vcc, 0, v16
	v_xor_b32_e32 v34, -1, v18
	v_xor_b32_e32 v35, -1, v17
	v_cndmask_b32_e32 v16, v33, v32, vcc
	v_and_b32_e32 v33, 0x7fffffff, v18
	v_and_b32_e32 v32, 0x7fffffff, v17
	v_pk_add_f32 v[32:33], v[32:33], 0 neg_lo:[1,1] neg_hi:[1,1]
	v_cmp_gt_i32_e32 vcc, 0, v18
	v_and_b32_e32 v16, 0xffffff80, v16
	v_bitop3_b32 v16, v16, s25, v68 bitop3:0x36
	v_cndmask_b32_e32 v18, v33, v34, vcc
	v_cmp_gt_i32_e32 vcc, 0, v17
	v_or_b32_e32 v33, 0x80000000, v19
	v_and_b32_e32 v18, 0xffffff80, v18
	v_cndmask_b32_e32 v17, v32, v35, vcc
	v_not_b32_e32 v32, v19
	v_cmp_gt_i32_e32 vcc, 0, v19
	v_and_b32_e32 v17, 0xffffff80, v17
	v_sub_u32_e32 v17, v17, v68
	v_cndmask_b32_e32 v19, v33, v32, vcc
	v_and_b32_e32 v19, 0xffffff80, v19
	v_sub_u32_e32 v18, v18, v69
	v_sub_u32_e32 v19, v19, v68
	v_add_u32_e32 v18, 0x7d, v18
	v_add_u32_e32 v17, 0x7e, v17
	v_add_u32_e32 v19, 0x7c, v19
	ds_write_b128 v108, v[16:19] offset:16384
	v_not_b32_e32 v16, v20
	v_or_b32_e32 v17, 0x80000000, v20
	v_cmp_gt_i32_e32 vcc, 0, v20
	v_and_b32_e32 v19, 0x7fffffff, v22
	v_and_b32_e32 v18, 0x7fffffff, v21
	v_mfma_f32_32x32x16_bf16 v[0:15], v[164:167], v[194:197], v[0:15]
	v_cndmask_b32_e32 v16, v17, v16, vcc
	v_xor_b32_e32 v17, -1, v22
	v_add_f32_e64 v18, -v18, neg(0)
	v_add_f32_e64 v19, -v19, neg(0)
	v_cmp_gt_i32_e32 vcc, 0, v22
	v_xor_b32_e32 v20, -1, v21
	v_and_b32_e32 v16, 0xffffff80, v16
	v_cndmask_b32_e32 v17, v19, v17, vcc
	v_cmp_gt_i32_e32 vcc, 0, v21
	v_and_b32_e32 v17, 0xffffff80, v17
	v_sub_u32_e32 v17, v17, v71
	v_cndmask_b32_e32 v18, v18, v20, vcc
	v_and_b32_e32 v18, 0xffffff80, v18
	v_sub_u32_e32 v19, v18, v70
	v_add_u32_e32 v18, 0x7d, v17
	v_add_u32_e32 v17, 0x7e, v19
	v_not_b32_e32 v19, v23
	v_or_b32_e32 v20, 0x80000000, v23
	v_cmp_gt_i32_e32 vcc, 0, v23
	v_mfma_f32_32x32x16_bf16 v[0:15], v[186:189], v[198:201], v[0:15]
	v_bitop3_b32 v16, v16, s27, v68 bitop3:0x36
	v_cndmask_b32_e32 v19, v20, v19, vcc
	v_and_b32_e32 v19, 0xffffff80, v19
	v_sub_u32_e32 v19, v19, v70
	v_add_u32_e32 v19, 0x7c, v19
	ds_write_b128 v109, v[16:19] offset:16384
	v_not_b32_e32 v16, v24
	v_or_b32_e32 v17, 0x80000000, v24
	v_cmp_gt_i32_e32 vcc, 0, v24
	v_and_b32_e32 v19, 0x7fffffff, v26
	v_and_b32_e32 v18, 0x7fffffff, v25
	v_cndmask_b32_e32 v16, v17, v16, vcc
	v_xor_b32_e32 v17, -1, v26
	v_pk_add_f32 v[18:19], v[18:19], 0 neg_lo:[1,1] neg_hi:[1,1]
	v_cmp_gt_i32_e32 vcc, 0, v26
	v_xor_b32_e32 v20, -1, v25
	v_mfma_f32_32x32x16_bf16 v[0:15], v[224:227], v[216:219], v[0:15]
	v_cndmask_b32_e32 v17, v19, v17, vcc
	v_cmp_gt_i32_e32 vcc, 0, v25
	v_and_b32_e32 v17, 0xffffff80, v17
	v_sub_u32_e32 v17, v17, v73
	v_cndmask_b32_e32 v18, v18, v20, vcc
	v_and_b32_e32 v18, 0xffffff80, v18
	v_sub_u32_e32 v19, v18, v72
	v_add_u32_e32 v18, 0x7d, v17
	v_add_u32_e32 v17, 0x7e, v19
	v_not_b32_e32 v19, v27
	v_or_b32_e32 v20, 0x80000000, v27
	v_cmp_gt_i32_e32 vcc, 0, v27
	v_and_b32_e32 v16, 0xffffff80, v16
	v_bitop3_b32 v16, v16, s28, v68 bitop3:0x36
	v_cndmask_b32_e32 v19, v20, v19, vcc
	v_and_b32_e32 v19, 0xffffff80, v19
	v_sub_u32_e32 v19, v19, v72
	v_add_u32_e32 v19, 0x7c, v19
	ds_write_b128 v110, v[16:19] offset:16384
	v_not_b32_e32 v16, v28
	v_or_b32_e32 v17, 0x80000000, v28
	v_cmp_gt_i32_e32 vcc, 0, v28
	v_and_b32_e32 v19, 0x7fffffff, v30
	v_and_b32_e32 v18, 0x7fffffff, v29
	v_cndmask_b32_e32 v16, v17, v16, vcc
	v_xor_b32_e32 v17, -1, v30
	v_pk_add_f32 v[18:19], v[18:19], 0 neg_lo:[1,1] neg_hi:[1,1]
	v_cmp_gt_i32_e32 vcc, 0, v30
	v_xor_b32_e32 v20, -1, v29
	v_mfma_f32_32x32x16_bf16 v[0:15], v[228:231], v[220:223], v[0:15]
	v_cndmask_b32_e32 v17, v19, v17, vcc
	v_cmp_gt_i32_e32 vcc, 0, v29
	v_and_b32_e32 v17, 0xffffff80, v17
	v_sub_u32_e32 v17, v17, v75
	v_cndmask_b32_e32 v18, v18, v20, vcc
	v_and_b32_e32 v18, 0xffffff80, v18
	v_sub_u32_e32 v19, v18, v74
	v_add_u32_e32 v18, 0x7d, v17
	v_add_u32_e32 v17, 0x7e, v19
	v_not_b32_e32 v19, v31
	v_or_b32_e32 v20, 0x80000000, v31
	v_cmp_gt_i32_e32 vcc, 0, v31
	v_and_b32_e32 v16, 0xffffff80, v16
	v_bitop3_b32 v16, v16, s29, v68 bitop3:0x36
	v_cndmask_b32_e32 v19, v20, v19, vcc
	v_and_b32_e32 v19, 0xffffff80, v19
	v_sub_u32_e32 v19, v19, v74
	v_add_u32_e32 v19, 0x7c, v19
	ds_write_b128 v111, v[16:19] offset:16384
	v_not_b32_e32 v16, v0
	v_or_b32_e32 v17, 0x80000000, v0
	v_cmp_gt_i32_e32 vcc, 0, v0
	v_xor_b32_e32 v18, -1, v2
	v_xor_b32_e32 v19, -1, v1
	v_cndmask_b32_e32 v0, v17, v16, vcc
	v_and_b32_e32 v17, 0x7fffffff, v2
	v_and_b32_e32 v16, 0x7fffffff, v1
	v_pk_add_f32 v[16:17], v[16:17], 0 neg_lo:[1,1] neg_hi:[1,1]
	v_cmp_gt_i32_e32 vcc, 0, v2
	v_and_b32_e32 v0, 0xffffff80, v0
	v_bitop3_b32 v0, v0, s22, v68 bitop3:0x36
	v_cndmask_b32_e32 v2, v17, v18, vcc
	v_cmp_gt_i32_e32 vcc, 0, v1
	v_or_b32_e32 v17, 0x80000000, v3
	v_and_b32_e32 v2, 0xffffff80, v2
	v_cndmask_b32_e32 v1, v16, v19, vcc
	v_not_b32_e32 v16, v3
	v_cmp_gt_i32_e32 vcc, 0, v3
	v_and_b32_e32 v1, 0xffffff80, v1
	v_sub_u32_e32 v1, v1, v76
	v_cndmask_b32_e32 v3, v17, v16, vcc
	v_and_b32_e32 v3, 0xffffff80, v3
	v_sub_u32_e32 v2, v2, v77
	v_sub_u32_e32 v3, v3, v76
	v_add_u32_e32 v2, 0x7d, v2
	v_add_u32_e32 v1, 0x7e, v1
	v_add_u32_e32 v3, 0x7c, v3
	ds_write_b128 v112, v[0:3] offset:16384
	v_not_b32_e32 v0, v4
	v_or_b32_e32 v1, 0x80000000, v4
	v_cmp_gt_i32_e32 vcc, 0, v4
	v_and_b32_e32 v3, 0x7fffffff, v6
	v_and_b32_e32 v2, 0x7fffffff, v5
	v_cndmask_b32_e32 v0, v1, v0, vcc
	v_xor_b32_e32 v1, -1, v6
	v_pk_add_f32 v[2:3], v[2:3], 0 neg_lo:[1,1] neg_hi:[1,1]
	v_cmp_gt_i32_e32 vcc, 0, v6
	v_xor_b32_e32 v4, -1, v5
	v_and_b32_e32 v0, 0xffffff80, v0
	v_cndmask_b32_e32 v1, v3, v1, vcc
	v_cmp_gt_i32_e32 vcc, 0, v5
	v_and_b32_e32 v1, 0xffffff80, v1
	v_sub_u32_e32 v1, v1, v79
	v_cndmask_b32_e32 v2, v2, v4, vcc
	v_and_b32_e32 v2, 0xffffff80, v2
	v_sub_u32_e32 v3, v2, v78
	v_add_u32_e32 v2, 0x7d, v1
	v_add_u32_e32 v1, 0x7e, v3
	v_not_b32_e32 v3, v7
	v_or_b32_e32 v4, 0x80000000, v7
	v_cmp_gt_i32_e32 vcc, 0, v7
	v_bitop3_b32 v0, v0, s35, v68 bitop3:0x36
	s_nop 0
	v_cndmask_b32_e32 v3, v4, v3, vcc
	v_and_b32_e32 v3, 0xffffff80, v3
	v_sub_u32_e32 v3, v3, v78
	v_add_u32_e32 v3, 0x7c, v3
	ds_write_b128 v113, v[0:3] offset:16384
	v_not_b32_e32 v0, v8
	v_or_b32_e32 v1, 0x80000000, v8
	v_cmp_gt_i32_e32 vcc, 0, v8
	v_and_b32_e32 v3, 0x7fffffff, v10
	v_and_b32_e32 v2, 0x7fffffff, v9
	v_cndmask_b32_e32 v0, v1, v0, vcc
	v_xor_b32_e32 v1, -1, v10
	v_pk_add_f32 v[2:3], v[2:3], 0 neg_lo:[1,1] neg_hi:[1,1]
	v_cmp_gt_i32_e32 vcc, 0, v10
	v_xor_b32_e32 v4, -1, v9
	v_and_b32_e32 v0, 0xffffff80, v0
	v_cndmask_b32_e32 v1, v3, v1, vcc
	v_cmp_gt_i32_e32 vcc, 0, v9
	v_and_b32_e32 v1, 0xffffff80, v1
	v_sub_u32_e32 v1, v1, v81
	v_cndmask_b32_e32 v2, v2, v4, vcc
	v_and_b32_e32 v2, 0xffffff80, v2
	v_sub_u32_e32 v3, v2, v80
	v_add_u32_e32 v2, 0x7d, v1
	v_add_u32_e32 v1, 0x7e, v3
	v_not_b32_e32 v3, v11
	v_or_b32_e32 v4, 0x80000000, v11
	v_cmp_gt_i32_e32 vcc, 0, v11
	v_bitop3_b32 v0, v0, s40, v68 bitop3:0x36
	s_nop 0
	v_cndmask_b32_e32 v3, v4, v3, vcc
	v_and_b32_e32 v3, 0xffffff80, v3
	v_sub_u32_e32 v3, v3, v80
	v_add_u32_e32 v3, 0x7c, v3
	ds_write_b128 v114, v[0:3] offset:16384
	v_not_b32_e32 v0, v12
	v_or_b32_e32 v1, 0x80000000, v12
	v_cmp_gt_i32_e32 vcc, 0, v12
	v_and_b32_e32 v3, 0x7fffffff, v14
	v_and_b32_e32 v2, 0x7fffffff, v13
	v_cndmask_b32_e32 v0, v1, v0, vcc
	v_xor_b32_e32 v1, -1, v14
	v_pk_add_f32 v[2:3], v[2:3], 0 neg_lo:[1,1] neg_hi:[1,1]
	v_cmp_gt_i32_e32 vcc, 0, v14
	v_xor_b32_e32 v4, -1, v13
	v_and_b32_e32 v0, 0xffffff80, v0
	v_cndmask_b32_e32 v1, v3, v1, vcc
	v_cmp_gt_i32_e32 vcc, 0, v13
	v_and_b32_e32 v1, 0xffffff80, v1
	v_sub_u32_e32 v1, v1, v83
	v_cndmask_b32_e32 v2, v2, v4, vcc
	v_and_b32_e32 v2, 0xffffff80, v2
	v_sub_u32_e32 v3, v2, v82
	v_add_u32_e32 v2, 0x7d, v1
	v_add_u32_e32 v1, 0x7e, v3
	v_not_b32_e32 v3, v15
	v_or_b32_e32 v4, 0x80000000, v15
	v_cmp_gt_i32_e32 vcc, 0, v15
	v_bitop3_b32 v0, v0, s41, v68 bitop3:0x36
	s_nop 0
	v_cndmask_b32_e32 v3, v4, v3, vcc
	v_and_b32_e32 v3, 0xffffff80, v3
	v_sub_u32_e32 v3, v3, v82
	v_add_u32_e32 v3, 0x7c, v3
	ds_write_b128 v115, v[0:3] offset:16384
	s_waitcnt lgkmcnt(0)
	s_barrier
	ds_read_b128 v[0:3], v116
	ds_read_b128 v[4:7], v117
	ds_read_b128 v[8:11], v118
	ds_read_b128 v[12:15], v119
	ds_read_b128 v[16:19], v120
	ds_read_b128 v[20:23], v121
	ds_read_b128 v[24:27], v122
	ds_read_b128 v[28:31], v123
	ds_read_b128 v[32:35], v124
	ds_read_b128 v[36:39], v125
	ds_read_b128 v[40:43], v126
	ds_read_b128 v[44:47], v127
	ds_read_b128 v[48:51], v128
	ds_read_b128 v[52:55], v129
	ds_read_b128 v[56:59], v130
	ds_read_b128 v[60:63], v131
	s_waitcnt lgkmcnt(0)
	s_barrier
	v_max_u32_e32 v212, v0, v1
	v_min_u32_e32 v1, v0, v1
	v_max_u32_e32 v0, v16, v17
	v_min_u32_e32 v17, v16, v17
	v_max_u32_e32 v16, v32, v33
	v_min_u32_e32 v33, v32, v33
	v_max_u32_e32 v32, v48, v49
	v_min_u32_e32 v49, v48, v49
	v_max_u32_e32 v48, v2, v3
	v_min_u32_e32 v3, v2, v3
	v_max_u32_e32 v2, v18, v19
	v_min_u32_e32 v19, v18, v19
	v_max_u32_e32 v18, v34, v35
	v_min_u32_e32 v35, v34, v35
	v_max_u32_e32 v34, v50, v51
	v_min_u32_e32 v51, v50, v51
	v_max_u32_e32 v50, v212, v48
	v_min_u32_e32 v48, v212, v48
	v_max_u32_e32 v212, v0, v2
	v_min_u32_e32 v2, v0, v2
	v_max_u32_e32 v0, v16, v18
	v_min_u32_e32 v18, v16, v18
	v_max_u32_e32 v16, v32, v34
	v_min_u32_e32 v34, v32, v34
	v_max_u32_e32 v32, v1, v3
	v_min_u32_e32 v3, v1, v3
	v_max_u32_e32 v1, v17, v19
	v_min_u32_e32 v19, v17, v19
	v_max_u32_e32 v17, v33, v35
	v_min_u32_e32 v35, v33, v35
	v_max_u32_e32 v33, v49, v51
	v_min_u32_e32 v51, v49, v51
	v_max_u32_e32 v49, v32, v48
	v_min_u32_e32 v48, v32, v48
	v_max_u32_e32 v32, v1, v2
	v_min_u32_e32 v2, v1, v2
	v_max_u32_e32 v1, v17, v18
	v_min_u32_e32 v18, v17, v18
	v_max_u32_e32 v17, v33, v34
	v_min_u32_e32 v34, v33, v34
	v_max_u32_e32 v33, v4, v5
	v_min_u32_e32 v5, v4, v5
	v_max_u32_e32 v4, v20, v21
	v_min_u32_e32 v21, v20, v21
	v_max_u32_e32 v20, v36, v37
	v_min_u32_e32 v37, v36, v37
	v_max_u32_e32 v36, v52, v53
	v_min_u32_e32 v53, v52, v53
	v_max_u32_e32 v52, v6, v7
	v_min_u32_e32 v7, v6, v7
	v_max_u32_e32 v6, v22, v23
	v_min_u32_e32 v23, v22, v23
	v_max_u32_e32 v22, v38, v39
	v_min_u32_e32 v39, v38, v39
	v_max_u32_e32 v38, v54, v55
	v_min_u32_e32 v55, v54, v55
	v_max_u32_e32 v54, v33, v52
	v_min_u32_e32 v52, v33, v52
	v_max_u32_e32 v33, v4, v6
	v_min_u32_e32 v6, v4, v6
	v_max_u32_e32 v4, v20, v22
	v_min_u32_e32 v22, v20, v22
	v_max_u32_e32 v20, v36, v38
	v_min_u32_e32 v38, v36, v38
	v_max_u32_e32 v36, v5, v7
	v_min_u32_e32 v7, v5, v7
	v_max_u32_e32 v5, v21, v23
	v_min_u32_e32 v23, v21, v23
	v_max_u32_e32 v21, v37, v39
	v_min_u32_e32 v39, v37, v39
	v_max_u32_e32 v37, v53, v55
	v_min_u32_e32 v55, v53, v55
	v_max_u32_e32 v53, v36, v52
	v_min_u32_e32 v52, v36, v52
	v_max_u32_e32 v36, v5, v6
	v_min_u32_e32 v6, v5, v6
	v_max_u32_e32 v5, v21, v22
	v_min_u32_e32 v22, v21, v22
	v_max_u32_e32 v21, v37, v38
	v_min_u32_e32 v38, v37, v38
	v_max_u32_e32 v37, v50, v54
	v_min_u32_e32 v54, v50, v54
	v_max_u32_e32 v50, v212, v33
	v_min_u32_e32 v33, v212, v33
	v_max_u32_e32 v212, v0, v4
	v_min_u32_e32 v4, v0, v4
	v_max_u32_e32 v0, v16, v20
	v_min_u32_e32 v20, v16, v20
	v_max_u32_e32 v16, v48, v52
	v_min_u32_e32 v52, v48, v52
	v_max_u32_e32 v48, v2, v6
	v_min_u32_e32 v6, v2, v6
	v_max_u32_e32 v2, v18, v22
	v_min_u32_e32 v22, v18, v22
	v_max_u32_e32 v18, v34, v38
	v_min_u32_e32 v38, v34, v38
	v_max_u32_e32 v34, v16, v54
	v_min_u32_e32 v54, v16, v54
	v_max_u32_e32 v16, v48, v33
	v_min_u32_e32 v33, v48, v33
	v_max_u32_e32 v48, v2, v4
	v_min_u32_e32 v4, v2, v4
	v_max_u32_e32 v2, v18, v20
	v_min_u32_e32 v20, v18, v20
	v_max_u32_e32 v18, v49, v53
	v_min_u32_e32 v53, v49, v53
	v_max_u32_e32 v49, v32, v36
	v_min_u32_e32 v36, v32, v36
	v_max_u32_e32 v32, v1, v5
	v_min_u32_e32 v5, v1, v5
	v_max_u32_e32 v1, v17, v21
	v_min_u32_e32 v21, v17, v21
	v_max_u32_e32 v17, v3, v7
	v_min_u32_e32 v7, v3, v7
	v_max_u32_e32 v3, v19, v23
	v_min_u32_e32 v23, v19, v23
	v_max_u32_e32 v19, v35, v39
	v_min_u32_e32 v39, v35, v39
	v_max_u32_e32 v35, v51, v55
	v_min_u32_e32 v55, v51, v55
	v_max_u32_e32 v51, v17, v53
	v_min_u32_e32 v53, v17, v53
	v_max_u32_e32 v17, v3, v36
	v_min_u32_e32 v36, v3, v36
	v_max_u32_e32 v3, v19, v5
	v_min_u32_e32 v5, v19, v5
	v_max_u32_e32 v19, v35, v21
	v_min_u32_e32 v21, v35, v21
	v_max_u32_e32 v35, v18, v34
	v_min_u32_e32 v34, v18, v34
	v_max_u32_e32 v18, v49, v16
	v_min_u32_e32 v16, v49, v16
	v_max_u32_e32 v49, v32, v48
	v_min_u32_e32 v48, v32, v48
	v_max_u32_e32 v32, v1, v2
	v_min_u32_e32 v2, v1, v2
	v_max_u32_e32 v1, v51, v54
	v_min_u32_e32 v54, v51, v54
	v_max_u32_e32 v51, v17, v33
	v_min_u32_e32 v33, v17, v33
	v_max_u32_e32 v17, v3, v4
	v_min_u32_e32 v4, v3, v4
	v_max_u32_e32 v3, v19, v20
	v_min_u32_e32 v20, v19, v20
	v_max_u32_e32 v19, v53, v52
	v_min_u32_e32 v52, v53, v52
	v_max_u32_e32 v53, v36, v6
	v_min_u32_e32 v6, v36, v6
	v_max_u32_e32 v36, v5, v22
	v_min_u32_e32 v22, v5, v22
	v_max_u32_e32 v5, v21, v38
	v_min_u32_e32 v38, v21, v38
	v_max_u32_e32 v21, v8, v9
	v_min_u32_e32 v9, v8, v9
	v_max_u32_e32 v8, v24, v25
	v_min_u32_e32 v25, v24, v25
	v_max_u32_e32 v24, v40, v41
	v_min_u32_e32 v41, v40, v41
	v_max_u32_e32 v40, v56, v57
	v_min_u32_e32 v57, v56, v57
	v_max_u32_e32 v56, v10, v11
	v_min_u32_e32 v11, v10, v11
	v_max_u32_e32 v10, v26, v27
	v_min_u32_e32 v27, v26, v27
	v_max_u32_e32 v26, v42, v43
	v_min_u32_e32 v43, v42, v43
	v_max_u32_e32 v42, v58, v59
	v_min_u32_e32 v59, v58, v59
	v_max_u32_e32 v58, v21, v56
	v_min_u32_e32 v56, v21, v56
	v_max_u32_e32 v21, v8, v10
	v_min_u32_e32 v10, v8, v10
	v_max_u32_e32 v8, v24, v26
	v_min_u32_e32 v26, v24, v26
	v_max_u32_e32 v24, v40, v42
	v_min_u32_e32 v42, v40, v42
	v_max_u32_e32 v40, v9, v11
	v_min_u32_e32 v11, v9, v11
	v_max_u32_e32 v9, v25, v27
	v_min_u32_e32 v27, v25, v27
	v_max_u32_e32 v25, v41, v43
	v_min_u32_e32 v43, v41, v43
	v_max_u32_e32 v41, v57, v59
	v_min_u32_e32 v59, v57, v59
	v_max_u32_e32 v57, v40, v56
	v_min_u32_e32 v56, v40, v56
	v_max_u32_e32 v40, v9, v10
	v_min_u32_e32 v10, v9, v10
	v_max_u32_e32 v9, v25, v26
	v_min_u32_e32 v26, v25, v26
	v_max_u32_e32 v25, v41, v42
	v_min_u32_e32 v42, v41, v42
	v_max_u32_e32 v41, v12, v13
	v_min_u32_e32 v13, v12, v13
	v_max_u32_e32 v12, v28, v29
	v_min_u32_e32 v29, v28, v29
	v_max_u32_e32 v28, v44, v45
	v_min_u32_e32 v45, v44, v45
	v_max_u32_e32 v44, v60, v61
	v_min_u32_e32 v61, v60, v61
	v_max_u32_e32 v60, v14, v15
	v_min_u32_e32 v15, v14, v15
	v_max_u32_e32 v14, v30, v31
	v_min_u32_e32 v31, v30, v31
	v_max_u32_e32 v30, v46, v47
	v_min_u32_e32 v47, v46, v47
	v_max_u32_e32 v46, v62, v63
	v_min_u32_e32 v63, v62, v63
	v_max_u32_e32 v62, v41, v60
	v_min_u32_e32 v60, v41, v60
	v_max_u32_e32 v41, v12, v14
	v_min_u32_e32 v14, v12, v14
	v_max_u32_e32 v12, v28, v30
	v_min_u32_e32 v30, v28, v30
	v_max_u32_e32 v28, v44, v46
	v_min_u32_e32 v46, v44, v46
	v_max_u32_e32 v44, v13, v15
	v_min_u32_e32 v15, v13, v15
	v_max_u32_e32 v13, v29, v31
	v_min_u32_e32 v31, v29, v31
	v_max_u32_e32 v29, v45, v47
	v_min_u32_e32 v47, v45, v47
	v_max_u32_e32 v45, v61, v63
	v_min_u32_e32 v63, v61, v63
	v_max_u32_e32 v61, v44, v60
	v_min_u32_e32 v60, v44, v60
	v_max_u32_e32 v44, v13, v14
	v_min_u32_e32 v14, v13, v14
	v_max_u32_e32 v13, v29, v30
	v_min_u32_e32 v30, v29, v30
	v_max_u32_e32 v29, v45, v46
	v_min_u32_e32 v46, v45, v46
	v_max_u32_e32 v45, v58, v62
	v_min_u32_e32 v62, v58, v62
	v_max_u32_e32 v58, v21, v41
	v_min_u32_e32 v41, v21, v41
	v_max_u32_e32 v21, v8, v12
	v_min_u32_e32 v12, v8, v12
	v_max_u32_e32 v8, v24, v28
	v_min_u32_e32 v28, v24, v28
	v_max_u32_e32 v24, v56, v60
	v_min_u32_e32 v60, v56, v60
	v_max_u32_e32 v56, v10, v14
	v_min_u32_e32 v14, v10, v14
	v_max_u32_e32 v10, v26, v30
	v_min_u32_e32 v30, v26, v30
	v_max_u32_e32 v26, v42, v46
	v_min_u32_e32 v46, v42, v46
	v_max_u32_e32 v42, v24, v62
	v_min_u32_e32 v62, v24, v62
	v_max_u32_e32 v24, v56, v41
	v_min_u32_e32 v41, v56, v41
	v_max_u32_e32 v56, v10, v12
	v_min_u32_e32 v12, v10, v12
	v_max_u32_e32 v10, v26, v28
	v_min_u32_e32 v28, v26, v28
	v_max_u32_e32 v26, v57, v61
	v_min_u32_e32 v61, v57, v61
	v_max_u32_e32 v57, v40, v44
	v_min_u32_e32 v44, v40, v44
	v_max_u32_e32 v40, v9, v13
	v_min_u32_e32 v13, v9, v13
	v_max_u32_e32 v9, v25, v29
	v_min_u32_e32 v29, v25, v29
	v_max_u32_e32 v25, v11, v15
	v_min_u32_e32 v15, v11, v15
	v_max_u32_e32 v11, v27, v31
	v_min_u32_e32 v31, v27, v31
	v_max_u32_e32 v27, v43, v47
	v_min_u32_e32 v47, v43, v47
	v_max_u32_e32 v43, v59, v63
	v_min_u32_e32 v63, v59, v63
	v_max_u32_e32 v59, v25, v61
	v_min_u32_e32 v61, v25, v61
	v_max_u32_e32 v25, v11, v44
	v_min_u32_e32 v44, v11, v44
	v_max_u32_e32 v11, v27, v13
	v_min_u32_e32 v13, v27, v13
	v_max_u32_e32 v27, v43, v29
	v_min_u32_e32 v29, v43, v29
	v_max_u32_e32 v43, v26, v42
	v_min_u32_e32 v42, v26, v42
	v_max_u32_e32 v26, v57, v24
	v_min_u32_e32 v24, v57, v24
	v_max_u32_e32 v57, v40, v56
	v_min_u32_e32 v56, v40, v56
	v_max_u32_e32 v40, v9, v10
	v_min_u32_e32 v10, v9, v10
	v_max_u32_e32 v9, v59, v62
	v_min_u32_e32 v62, v59, v62
	v_max_u32_e32 v59, v25, v41
	v_min_u32_e32 v41, v25, v41
	v_max_u32_e32 v25, v11, v12
	v_min_u32_e32 v12, v11, v12
	v_max_u32_e32 v11, v27, v28
	v_min_u32_e32 v28, v27, v28
	v_max_u32_e32 v27, v61, v60
	v_min_u32_e32 v60, v61, v60
	v_max_u32_e32 v61, v44, v14
	v_min_u32_e32 v14, v44, v14
	v_max_u32_e32 v44, v13, v30
	v_min_u32_e32 v30, v13, v30
	v_max_u32_e32 v13, v29, v46
	v_min_u32_e32 v46, v29, v46
	v_max_u32_e32 v29, v37, v45
	v_min_u32_e32 v45, v37, v45
	v_max_u32_e32 v37, v50, v58
	v_min_u32_e32 v58, v50, v58
	v_max_u32_e32 v50, v212, v21
	v_min_u32_e32 v21, v212, v21
	v_max_u32_e32 v212, v0, v8
	v_min_u32_e32 v8, v0, v8
	v_max_u32_e32 v0, v54, v62
	v_min_u32_e32 v62, v54, v62
	v_max_u32_e32 v54, v33, v41
	v_min_u32_e32 v41, v33, v41
	v_max_u32_e32 v33, v4, v12
	v_min_u32_e32 v12, v4, v12
	v_max_u32_e32 v4, v20, v28
	v_min_u32_e32 v28, v20, v28
	v_max_u32_e32 v20, v0, v45
	v_min_u32_e32 v45, v0, v45
	v_max_u32_e32 v0, v54, v58
	v_min_u32_e32 v58, v54, v58
	v_max_u32_e32 v54, v33, v21
	v_min_u32_e32 v21, v33, v21
	v_max_u32_e32 v33, v4, v8
	v_min_u32_e32 v8, v4, v8
	v_max_u32_e32 v4, v34, v42
	v_min_u32_e32 v42, v34, v42
	v_max_u32_e32 v34, v16, v24
	v_min_u32_e32 v24, v16, v24
	v_max_u32_e32 v16, v48, v56
	v_min_u32_e32 v56, v48, v56
	v_max_u32_e32 v48, v2, v10
	v_min_u32_e32 v10, v2, v10
	v_max_u32_e32 v2, v52, v60
	v_min_u32_e32 v60, v52, v60
	v_max_u32_e32 v52, v6, v14
	v_min_u32_e32 v14, v6, v14
	v_max_u32_e32 v6, v22, v30
	v_min_u32_e32 v30, v22, v30
	v_max_u32_e32 v22, v38, v46
	v_min_u32_e32 v46, v38, v46
	v_max_u32_e32 v38, v2, v42
	v_min_u32_e32 v42, v2, v42
	v_max_u32_e32 v2, v52, v24
	v_min_u32_e32 v24, v52, v24
	v_max_u32_e32 v52, v6, v56
	v_min_u32_e32 v56, v6, v56
	v_max_u32_e32 v6, v22, v10
	v_min_u32_e32 v10, v22, v10
	v_max_u32_e32 v22, v4, v20
	v_min_u32_e32 v20, v4, v20
	v_max_u32_e32 v4, v34, v0
	v_min_u32_e32 v0, v34, v0
	v_max_u32_e32 v34, v16, v54
	v_min_u32_e32 v54, v16, v54
	v_max_u32_e32 v16, v48, v33
	v_min_u32_e32 v33, v48, v33
	v_max_u32_e32 v48, v38, v45
	v_min_u32_e32 v45, v38, v45
	v_max_u32_e32 v38, v2, v58
	v_min_u32_e32 v58, v2, v58
	v_max_u32_e32 v2, v52, v21
	v_min_u32_e32 v21, v52, v21
	v_max_u32_e32 v52, v6, v8
	v_min_u32_e32 v8, v6, v8
	v_max_u32_e32 v6, v42, v62
	v_min_u32_e32 v62, v42, v62
	v_max_u32_e32 v42, v24, v41
	v_min_u32_e32 v41, v24, v41
	v_max_u32_e32 v24, v56, v12
	v_min_u32_e32 v12, v56, v12
	v_max_u32_e32 v56, v10, v28
	v_min_u32_e32 v28, v10, v28
	v_max_u32_e32 v10, v35, v43
	v_min_u32_e32 v43, v35, v43
	v_max_u32_e32 v35, v18, v26
	v_min_u32_e32 v26, v18, v26
	v_max_u32_e32 v18, v49, v57
	v_min_u32_e32 v57, v49, v57
	v_max_u32_e32 v49, v32, v40
	v_min_u32_e32 v40, v32, v40
	v_max_u32_e32 v32, v19, v27
	v_min_u32_e32 v27, v19, v27
	v_max_u32_e32 v19, v53, v61
	v_min_u32_e32 v61, v53, v61
	v_max_u32_e32 v53, v36, v44
	v_min_u32_e32 v44, v36, v44
	v_max_u32_e32 v36, v5, v13
	v_min_u32_e32 v13, v5, v13
	v_max_u32_e32 v5, v32, v43
	v_min_u32_e32 v43, v32, v43
	v_max_u32_e32 v32, v19, v26
	v_min_u32_e32 v26, v19, v26
	v_max_u32_e32 v19, v53, v57
	v_min_u32_e32 v57, v53, v57
	v_max_u32_e32 v53, v36, v40
	v_min_u32_e32 v40, v36, v40
	v_max_u32_e32 v36, v1, v9
	v_min_u32_e32 v9, v1, v9
	v_max_u32_e32 v1, v51, v59
	v_min_u32_e32 v59, v51, v59
	v_max_u32_e32 v51, v17, v25
	v_min_u32_e32 v25, v17, v25
	v_max_u32_e32 v17, v3, v11
	v_min_u32_e32 v11, v3, v11
	v_max_u32_e32 v3, v7, v15
	v_min_u32_e32 v15, v7, v15
	v_max_u32_e32 v7, v23, v31
	v_min_u32_e32 v31, v23, v31
	v_max_u32_e32 v23, v39, v47
	v_min_u32_e32 v47, v39, v47
	v_max_u32_e32 v39, v55, v63
	v_min_u32_e32 v63, v55, v63
	v_max_u32_e32 v55, v3, v9
	v_min_u32_e32 v9, v3, v9
	v_max_u32_e32 v3, v7, v59
	v_min_u32_e32 v59, v7, v59
	v_max_u32_e32 v7, v23, v25
	v_min_u32_e32 v25, v23, v25
	v_max_u32_e32 v23, v39, v11
	v_min_u32_e32 v11, v39, v11
	v_max_u32_e32 v39, v36, v5
	v_min_u32_e32 v5, v36, v5
	v_max_u32_e32 v36, v1, v32
	v_min_u32_e32 v32, v1, v32
	v_max_u32_e32 v1, v51, v19
	v_min_u32_e32 v19, v51, v19
	v_max_u32_e32 v51, v17, v53
	v_min_u32_e32 v53, v17, v53
	v_max_u32_e32 v17, v55, v43
	v_min_u32_e32 v43, v55, v43
	v_max_u32_e32 v55, v3, v26
	v_min_u32_e32 v26, v3, v26
	v_max_u32_e32 v3, v7, v57
	v_min_u32_e32 v57, v7, v57
	v_max_u32_e32 v7, v23, v40
	v_min_u32_e32 v40, v23, v40
	v_max_u32_e32 v23, v9, v27
	v_min_u32_e32 v27, v9, v27
	v_max_u32_e32 v9, v59, v61
	v_min_u32_e32 v61, v59, v61
	v_max_u32_e32 v59, v25, v44
	v_min_u32_e32 v44, v25, v44
	v_max_u32_e32 v25, v11, v13
	v_min_u32_e32 v13, v11, v13
	v_max_u32_e32 v11, v10, v22
	v_min_u32_e32 v22, v10, v22
	v_max_u32_e32 v10, v35, v4
	v_min_u32_e32 v4, v35, v4
	v_max_u32_e32 v35, v18, v34
	v_min_u32_e32 v34, v18, v34
	v_max_u32_e32 v18, v49, v16
	v_min_u32_e32 v16, v49, v16
	v_max_u32_e32 v49, v39, v20
	v_min_u32_e32 v20, v39, v20
	v_max_u32_e32 v39, v36, v0
	v_min_u32_e32 v0, v36, v0
	v_max_u32_e32 v36, v1, v54
	v_min_u32_e32 v54, v1, v54
	v_max_u32_e32 v1, v51, v33
	v_min_u32_e32 v33, v51, v33
	v_max_u32_e32 v51, v5, v48
	v_min_u32_e32 v48, v5, v48
	v_max_u32_e32 v5, v32, v38
	v_min_u32_e32 v38, v32, v38
	v_max_u32_e32 v32, v19, v2
	v_min_u32_e32 v2, v19, v2
	v_max_u32_e32 v19, v53, v52
	v_min_u32_e32 v52, v53, v52
	v_max_u32_e32 v53, v17, v45
	v_min_u32_e32 v45, v17, v45
	v_max_u32_e32 v17, v55, v58
	v_min_u32_e32 v58, v55, v58
	v_max_u32_e32 v55, v3, v21
	v_min_u32_e32 v21, v3, v21
	v_max_u32_e32 v3, v7, v8
	v_min_u32_e32 v8, v7, v8
	v_max_u32_e32 v7, v43, v6
	v_min_u32_e32 v6, v43, v6
	v_max_u32_e32 v43, v26, v42
	v_min_u32_e32 v42, v26, v42
	v_max_u32_e32 v26, v57, v24
	v_min_u32_e32 v24, v57, v24
	v_max_u32_e32 v57, v40, v56
	v_min_u32_e32 v56, v40, v56
	v_max_u32_e32 v40, v23, v62
	v_min_u32_e32 v62, v23, v62
	v_max_u32_e32 v23, v9, v41
	v_min_u32_e32 v41, v9, v41
	v_max_u32_e32 v9, v59, v12
	v_min_u32_e32 v12, v59, v12
	v_max_u32_e32 v59, v25, v28
	v_min_u32_e32 v28, v25, v28
	v_max_u32_e32 v25, v27, v60
	v_min_u32_e32 v60, v27, v60
	v_max_u32_e32 v27, v61, v14
	v_min_u32_e32 v14, v61, v14
	v_max_u32_e32 v61, v44, v30
	v_min_u32_e32 v30, v44, v30
	v_max_u32_e32 v44, v13, v46
	v_min_u32_e32 v46, v13, v46
	v_max_u32_e32 v29, v29, v31
	v_max_u32_e32 v11, v11, v14
	v_max_u32_e32 v22, v22, v27
	v_max_u32_e32 v49, v49, v41
	v_max_u32_e32 v20, v20, v23
	v_max_u32_e32 v51, v51, v42
	v_max_u32_e32 v48, v48, v43
	v_max_u32_e32 v53, v53, v58
	v_max_u32_e32 v45, v45, v17
	v_max_u32_e32 v7, v7, v38
	v_max_u32_e32 v6, v6, v5
	v_max_u32_e32 v40, v40, v0
	v_max_u32_e32 v62, v62, v39
	v_max_u32_e32 v25, v25, v4
	v_max_u32_e32 v60, v60, v10
	v_max_u32_e32 v15, v15, v37
	v_max_u32_e32 v13, v29, v45
	v_min_u32_e32 v45, v29, v45
	v_max_u32_e32 v29, v11, v7
	v_min_u32_e32 v7, v11, v7
	v_max_u32_e32 v11, v22, v6
	v_min_u32_e32 v6, v22, v6
	v_max_u32_e32 v22, v49, v40
	v_min_u32_e32 v40, v49, v40
	v_max_u32_e32 v49, v20, v62
	v_min_u32_e32 v62, v20, v62
	v_max_u32_e32 v20, v51, v25
	v_min_u32_e32 v25, v51, v25
	v_max_u32_e32 v51, v48, v60
	v_min_u32_e32 v60, v48, v60
	v_max_u32_e32 v48, v53, v15
	v_min_u32_e32 v15, v53, v15
	v_max_u32_e32 v53, v13, v49
	v_min_u32_e32 v49, v13, v49
	v_max_u32_e32 v13, v29, v20
	v_min_u32_e32 v20, v29, v20
	v_max_u32_e32 v29, v11, v51
	v_min_u32_e32 v51, v11, v51
	v_max_u32_e32 v11, v22, v48
	v_min_u32_e32 v48, v22, v48
	v_max_u32_e32 v22, v45, v62
	v_min_u32_e32 v62, v45, v62
	v_max_u32_e32 v45, v7, v25
	v_min_u32_e32 v25, v7, v25
	v_max_u32_e32 v7, v6, v60
	v_min_u32_e32 v60, v6, v60
	v_max_u32_e32 v6, v40, v15
	v_min_u32_e32 v15, v40, v15
	v_max_u32_e32 v40, v53, v29
	v_min_u32_e32 v29, v53, v29
	v_max_u32_e32 v53, v13, v11
	v_min_u32_e32 v11, v13, v11
	v_max_u32_e32 v13, v49, v51
	v_min_u32_e32 v51, v49, v51
	v_max_u32_e32 v49, v20, v48
	v_min_u32_e32 v48, v20, v48
	v_max_u32_e32 v20, v22, v7
	v_min_u32_e32 v7, v22, v7
	v_max_u32_e32 v22, v45, v6
	v_min_u32_e32 v6, v45, v6
	v_max_u32_e32 v45, v62, v60
	v_min_u32_e32 v60, v62, v60
	v_max_u32_e32 v62, v25, v15
	v_min_u32_e32 v15, v25, v15
	v_max_u32_e32 v25, v40, v53
	v_min_u32_e32 v53, v40, v53
	v_max_u32_e32 v40, v29, v11
	v_min_u32_e32 v11, v29, v11
	v_max_u32_e32 v29, v13, v49
	v_min_u32_e32 v49, v13, v49
	v_max_u32_e32 v13, v51, v48
	v_min_u32_e32 v48, v51, v48
	v_max_u32_e32 v51, v20, v22
	v_min_u32_e32 v22, v20, v22
	v_max_u32_e32 v20, v7, v6
	v_min_u32_e32 v6, v7, v6
	v_max_u32_e32 v7, v45, v62
	v_min_u32_e32 v62, v45, v62
	v_max_u32_e32 v45, v60, v15
	v_min_u32_e32 v15, v60, v15
	v_max_u32_e32 v50, v50, v63
	v_max_u32_e32 v35, v35, v46
	v_max_u32_e32 v34, v34, v44
	v_max_u32_e32 v36, v36, v28
	v_max_u32_e32 v54, v54, v59
	v_max_u32_e32 v32, v32, v56
	v_max_u32_e32 v2, v2, v57
	v_max_u32_e32 v55, v55, v8
	v_max_u32_e32 v21, v21, v3
	v_max_u32_e32 v26, v26, v52
	v_max_u32_e32 v24, v24, v19
	v_max_u32_e32 v9, v9, v33
	v_max_u32_e32 v12, v12, v1
	v_max_u32_e32 v61, v61, v16
	v_max_u32_e32 v30, v30, v18
	v_max_u32_e32 v47, v47, v212
	v_max_u32_e32 v60, v50, v21
	v_min_u32_e32 v21, v50, v21
	v_max_u32_e32 v50, v35, v26
	v_min_u32_e32 v26, v35, v26
	v_max_u32_e32 v35, v34, v24
	v_min_u32_e32 v24, v34, v24
	v_max_u32_e32 v34, v36, v9
	v_min_u32_e32 v9, v36, v9
	v_max_u32_e32 v36, v54, v12
	v_min_u32_e32 v12, v54, v12
	v_max_u32_e32 v54, v32, v61
	v_min_u32_e32 v61, v32, v61
	v_max_u32_e32 v32, v2, v30
	v_min_u32_e32 v30, v2, v30
	v_max_u32_e32 v2, v55, v47
	v_min_u32_e32 v47, v55, v47
	v_max_u32_e32 v55, v60, v36
	v_min_u32_e32 v36, v60, v36
	v_max_u32_e32 v60, v50, v54
	v_min_u32_e32 v54, v50, v54
	v_max_u32_e32 v50, v35, v32
	v_min_u32_e32 v32, v35, v32
	v_max_u32_e32 v35, v34, v2
	v_min_u32_e32 v2, v34, v2
	v_max_u32_e32 v34, v21, v12
	v_min_u32_e32 v12, v21, v12
	v_max_u32_e32 v21, v26, v61
	v_min_u32_e32 v61, v26, v61
	v_max_u32_e32 v26, v24, v30
	v_min_u32_e32 v30, v24, v30
	v_max_u32_e32 v24, v9, v47
	v_min_u32_e32 v47, v9, v47
	v_max_u32_e32 v9, v55, v50
	v_min_u32_e32 v50, v55, v50
	v_max_u32_e32 v55, v60, v35
	v_min_u32_e32 v35, v60, v35
	v_max_u32_e32 v60, v36, v32
	v_min_u32_e32 v32, v36, v32
	v_max_u32_e32 v36, v54, v2
	v_min_u32_e32 v2, v54, v2
	v_max_u32_e32 v54, v34, v26
	v_min_u32_e32 v26, v34, v26
	v_max_u32_e32 v34, v21, v24
	v_min_u32_e32 v24, v21, v24
	v_max_u32_e32 v21, v12, v30
	v_min_u32_e32 v30, v12, v30
	v_max_u32_e32 v12, v61, v47
	v_min_u32_e32 v47, v61, v47
	v_max_u32_e32 v61, v9, v55
	v_min_u32_e32 v55, v9, v55
	v_max_u32_e32 v9, v50, v35
	v_min_u32_e32 v35, v50, v35
	v_max_u32_e32 v50, v60, v36
	v_min_u32_e32 v36, v60, v36
	v_max_u32_e32 v60, v32, v2
	v_min_u32_e32 v2, v32, v2
	v_max_u32_e32 v32, v54, v34
	v_min_u32_e32 v34, v54, v34
	v_max_u32_e32 v54, v26, v24
	v_min_u32_e32 v24, v26, v24
	v_max_u32_e32 v26, v21, v12
	v_min_u32_e32 v12, v21, v12
	v_max_u32_e32 v21, v30, v47
	v_min_u32_e32 v47, v30, v47
	v_max_u32_e32 v25, v25, v47
	v_max_u32_e32 v53, v53, v21
	v_max_u32_e32 v40, v40, v12
	v_max_u32_e32 v11, v11, v26
	v_max_u32_e32 v29, v29, v24
	v_max_u32_e32 v49, v49, v54
	v_max_u32_e32 v13, v13, v34
	v_max_u32_e32 v48, v48, v32
	v_max_u32_e32 v51, v51, v2
	v_max_u32_e32 v22, v22, v60
	v_max_u32_e32 v20, v20, v36
	v_max_u32_e32 v6, v6, v50
	v_max_u32_e32 v7, v7, v35
	v_max_u32_e32 v62, v62, v9
	v_max_u32_e32 v45, v45, v55
	v_max_u32_e32 v15, v15, v61
	v_max_u32_e32 v30, v25, v51
	v_min_u32_e32 v51, v25, v51
	v_max_u32_e32 v25, v53, v22
	v_min_u32_e32 v22, v53, v22
	v_max_u32_e32 v53, v40, v20
	v_min_u32_e32 v20, v40, v20
	v_max_u32_e32 v40, v11, v6
	v_min_u32_e32 v6, v11, v6
	v_max_u32_e32 v11, v29, v7
	v_min_u32_e32 v7, v29, v7
	v_max_u32_e32 v29, v49, v62
	v_min_u32_e32 v62, v49, v62
	v_max_u32_e32 v49, v13, v45
	v_min_u32_e32 v45, v13, v45
	v_max_u32_e32 v13, v48, v15
	v_min_u32_e32 v15, v48, v15
	v_max_u32_e32 v48, v30, v11
	v_min_u32_e32 v11, v30, v11
	v_max_u32_e32 v30, v25, v29
	v_min_u32_e32 v29, v25, v29
	v_max_u32_e32 v25, v53, v49
	v_min_u32_e32 v49, v53, v49
	v_max_u32_e32 v53, v40, v13
	v_min_u32_e32 v13, v40, v13
	v_max_u32_e32 v40, v51, v7
	v_min_u32_e32 v7, v51, v7
	v_max_u32_e32 v51, v22, v62
	v_min_u32_e32 v62, v22, v62
	v_max_u32_e32 v22, v20, v45
	v_min_u32_e32 v45, v20, v45
	v_max_u32_e32 v20, v6, v15
	v_min_u32_e32 v15, v6, v15
	v_max_u32_e32 v6, v48, v25
	v_min_u32_e32 v25, v48, v25
	v_max_u32_e32 v48, v30, v53
	v_min_u32_e32 v53, v30, v53
	v_max_u32_e32 v30, v11, v49
	v_min_u32_e32 v49, v11, v49
	v_max_u32_e32 v11, v29, v13
	v_min_u32_e32 v13, v29, v13
	v_max_u32_e32 v29, v40, v22
	v_min_u32_e32 v22, v40, v22
	v_max_u32_e32 v40, v51, v20
	v_min_u32_e32 v20, v51, v20
	v_max_u32_e32 v51, v7, v45
	v_min_u32_e32 v45, v7, v45
	v_max_u32_e32 v7, v62, v15
	v_min_u32_e32 v15, v62, v15
	v_max_u32_e32 v62, v6, v48
	v_min_u32_e32 v48, v6, v48
	v_max_u32_e32 v6, v25, v53
	v_min_u32_e32 v53, v25, v53
	v_max_u32_e32 v25, v30, v11
	v_min_u32_e32 v11, v30, v11
	v_max_u32_e32 v30, v49, v13
	v_min_u32_e32 v13, v49, v13
	v_max_u32_e32 v49, v29, v40
	v_min_u32_e32 v40, v29, v40
	v_max_u32_e32 v29, v22, v20
	v_min_u32_e32 v20, v22, v20
	v_max_u32_e32 v22, v51, v7
	v_min_u32_e32 v7, v51, v7
	v_max_u32_e32 v51, v45, v15
	v_min_u32_e32 v15, v45, v15
	ds_write_b32 v106, v62
	ds_write_b32 v106, v48 offset:1024
	ds_write_b32 v106, v6 offset:2048
	ds_write_b32 v106, v53 offset:3072
	ds_write_b32 v106, v25 offset:4096
	ds_write_b32 v106, v11 offset:5120
	ds_write_b32 v106, v30 offset:6144
	ds_write_b32 v106, v13 offset:7168
	ds_write_b32 v106, v49 offset:8192
	ds_write_b32 v106, v40 offset:9216
	ds_write_b32 v106, v29 offset:10240
	ds_write_b32 v106, v20 offset:11264
	ds_write_b32 v106, v22 offset:12288
	ds_write_b32 v106, v7 offset:13312
	ds_write_b32 v106, v51 offset:14336
	ds_write_b32 v106, v15 offset:15360
	s_waitcnt lgkmcnt(0)
	s_barrier
	s_and_saveexec_b64 s[20:21], s[6:7]
	s_cbranch_execz .LBB0_1083
	s_and_b64 s[8:9], s[18:19], exec
	s_cselect_b32 s0, s23, s42
	s_cselect_b32 s8, s24, s43
	v_add_u32_e32 v216, s8, v156
	v_add_u32_e32 v217, s0, v162
	ds_read_b32 v218, v106 offset:512
	ds_read_b32 v219, v106 offset:1536
	ds_read_b32 v220, v106 offset:2560
	ds_read_b32 v221, v106 offset:3584
	ds_read_b32 v222, v106 offset:4608
	ds_read_b32 v223, v106 offset:5632
	ds_read_b32 v224, v106 offset:6656
	ds_read_b32 v225, v106 offset:7680
	ds_read_b32 v226, v106 offset:8704
	ds_read_b32 v227, v106 offset:9728
	ds_read_b32 v228, v106 offset:10752
	ds_read_b32 v229, v106 offset:11776
	ds_read_b32 v230, v106 offset:12800
	ds_read_b32 v231, v106 offset:13824
	ds_read_b32 v232, v106 offset:14848
	ds_read_b32 v233, v106 offset:15872
	s_waitcnt lgkmcnt(0)
	v_max_u32_e32 v62, v62, v233
	v_max_u32_e32 v48, v48, v232
	v_max_u32_e32 v6, v6, v231
	v_max_u32_e32 v53, v53, v230
	v_max_u32_e32 v25, v25, v229
	v_max_u32_e32 v11, v11, v228
	v_max_u32_e32 v30, v30, v227
	v_max_u32_e32 v13, v13, v226
	v_max_u32_e32 v49, v49, v225
	v_max_u32_e32 v40, v40, v224
	v_max_u32_e32 v29, v29, v223
	v_max_u32_e32 v20, v20, v222
	v_max_u32_e32 v22, v22, v221
	v_max_u32_e32 v7, v7, v220
	v_max_u32_e32 v51, v51, v219
	v_max_u32_e32 v15, v15, v218
	v_max_u32_e32 v45, v62, v49
	v_min_u32_e32 v49, v62, v49
	v_max_u32_e32 v62, v48, v40
	v_min_u32_e32 v40, v48, v40
	v_max_u32_e32 v48, v6, v29
	v_min_u32_e32 v29, v6, v29
	v_max_u32_e32 v6, v53, v20
	v_min_u32_e32 v20, v53, v20
	v_max_u32_e32 v53, v25, v22
	v_min_u32_e32 v22, v25, v22
	v_max_u32_e32 v25, v11, v7
	v_min_u32_e32 v7, v11, v7
	v_max_u32_e32 v11, v30, v51
	v_min_u32_e32 v51, v30, v51
	v_max_u32_e32 v30, v13, v15
	v_min_u32_e32 v15, v13, v15
	v_max_u32_e32 v13, v45, v53
	v_min_u32_e32 v53, v45, v53
	v_max_u32_e32 v45, v62, v25
	v_min_u32_e32 v25, v62, v25
	v_max_u32_e32 v62, v48, v11
	v_min_u32_e32 v11, v48, v11
	v_max_u32_e32 v48, v6, v30
	v_min_u32_e32 v30, v6, v30
	v_max_u32_e32 v6, v49, v22
	v_min_u32_e32 v22, v49, v22
	v_max_u32_e32 v49, v40, v7
	v_min_u32_e32 v7, v40, v7
	v_max_u32_e32 v40, v29, v51
	v_min_u32_e32 v51, v29, v51
	v_max_u32_e32 v29, v20, v15
	v_min_u32_e32 v15, v20, v15
	v_max_u32_e32 v20, v13, v62
	v_min_u32_e32 v62, v13, v62
	v_max_u32_e32 v13, v45, v48
	v_min_u32_e32 v48, v45, v48
	v_max_u32_e32 v45, v53, v11
	v_min_u32_e32 v11, v53, v11
	v_max_u32_e32 v53, v25, v30
	v_min_u32_e32 v30, v25, v30
	v_max_u32_e32 v25, v6, v40
	v_min_u32_e32 v40, v6, v40
	v_max_u32_e32 v6, v49, v29
	v_min_u32_e32 v29, v49, v29
	v_max_u32_e32 v49, v22, v51
	v_min_u32_e32 v51, v22, v51
	v_max_u32_e32 v22, v7, v15
	v_min_u32_e32 v15, v7, v15
	v_max_u32_e32 v7, v20, v13
	v_min_u32_e32 v13, v20, v13
	v_max_u32_e32 v20, v62, v48
	v_min_u32_e32 v48, v62, v48
	v_max_u32_e32 v62, v45, v53
	v_min_u32_e32 v53, v45, v53
	v_max_u32_e32 v45, v11, v30
	v_min_u32_e32 v30, v11, v30
	v_max_u32_e32 v11, v25, v6
	v_min_u32_e32 v6, v25, v6
	v_max_u32_e32 v25, v40, v29
	v_min_u32_e32 v29, v40, v29
	v_max_u32_e32 v40, v49, v22
	v_min_u32_e32 v22, v49, v22
	v_max_u32_e32 v49, v51, v15
	v_min_u32_e32 v15, v51, v15
	v_cmp_gt_i32_e32 vcc, 0, v7
	v_and_b32_e32 v213, 0x7fffff80, v7
	v_not_b32_e32 v214, v7
	v_or_b32_e32 v214, 0x7f, v214
	v_cndmask_b32_e32 v213, v214, v213, vcc
	v_not_b32_e32 v215, v7
	v_and_b32_e32 v215, 0x7f, v215
	ds_write_b32 v217, v213
	ds_write_b8 v216, v215
	v_cmp_gt_i32_e32 vcc, 0, v13
	v_and_b32_e32 v214, 0x7fffff80, v13
	v_not_b32_e32 v215, v13
	v_or_b32_e32 v215, 0x7f, v215
	v_cndmask_b32_e32 v214, v215, v214, vcc
	v_not_b32_e32 v213, v13
	v_and_b32_e32 v213, 0x7f, v213
	ds_write_b32 v217, v214 offset:512
	ds_write_b8 v216, v213 offset:128
	v_cmp_gt_i32_e32 vcc, 0, v20
	v_and_b32_e32 v215, 0x7fffff80, v20
	v_not_b32_e32 v213, v20
	v_or_b32_e32 v213, 0x7f, v213
	v_cndmask_b32_e32 v215, v213, v215, vcc
	v_not_b32_e32 v214, v20
	v_and_b32_e32 v214, 0x7f, v214
	ds_write_b32 v217, v215 offset:1024
	ds_write_b8 v216, v214 offset:256
	v_cmp_gt_i32_e32 vcc, 0, v48
	v_and_b32_e32 v213, 0x7fffff80, v48
	v_not_b32_e32 v214, v48
	v_or_b32_e32 v214, 0x7f, v214
	v_cndmask_b32_e32 v213, v214, v213, vcc
	v_not_b32_e32 v215, v48
	v_and_b32_e32 v215, 0x7f, v215
	ds_write_b32 v217, v213 offset:1536
	ds_write_b8 v216, v215 offset:384
	v_cmp_gt_i32_e32 vcc, 0, v62
	v_and_b32_e32 v214, 0x7fffff80, v62
	v_not_b32_e32 v215, v62
	v_or_b32_e32 v215, 0x7f, v215
	v_cndmask_b32_e32 v214, v215, v214, vcc
	v_not_b32_e32 v213, v62
	v_and_b32_e32 v213, 0x7f, v213
	ds_write_b32 v217, v214 offset:2048
	ds_write_b8 v216, v213 offset:512
	v_cmp_gt_i32_e32 vcc, 0, v53
	v_and_b32_e32 v215, 0x7fffff80, v53
	v_not_b32_e32 v213, v53
	v_or_b32_e32 v213, 0x7f, v213
	v_cndmask_b32_e32 v215, v213, v215, vcc
	v_not_b32_e32 v214, v53
	v_and_b32_e32 v214, 0x7f, v214
	ds_write_b32 v217, v215 offset:2560
	ds_write_b8 v216, v214 offset:640
	v_cmp_gt_i32_e32 vcc, 0, v45
	v_and_b32_e32 v213, 0x7fffff80, v45
	v_not_b32_e32 v214, v45
	v_or_b32_e32 v214, 0x7f, v214
	v_cndmask_b32_e32 v213, v214, v213, vcc
	v_not_b32_e32 v215, v45
	v_and_b32_e32 v215, 0x7f, v215
	ds_write_b32 v217, v213 offset:3072
	ds_write_b8 v216, v215 offset:768
	v_cmp_gt_i32_e32 vcc, 0, v30
	v_and_b32_e32 v214, 0x7fffff80, v30
	v_not_b32_e32 v215, v30
	v_or_b32_e32 v215, 0x7f, v215
	v_cndmask_b32_e32 v214, v215, v214, vcc
	v_not_b32_e32 v213, v30
	v_and_b32_e32 v213, 0x7f, v213
	ds_write_b32 v217, v214 offset:3584
	ds_write_b8 v216, v213 offset:896
	v_cmp_gt_i32_e32 vcc, 0, v11
	v_and_b32_e32 v215, 0x7fffff80, v11
	v_not_b32_e32 v213, v11
	v_or_b32_e32 v213, 0x7f, v213
	v_cndmask_b32_e32 v215, v213, v215, vcc
	v_not_b32_e32 v214, v11
	v_and_b32_e32 v214, 0x7f, v214
	ds_write_b32 v217, v215 offset:4096
	ds_write_b8 v216, v214 offset:1024
	v_cmp_gt_i32_e32 vcc, 0, v6
	v_and_b32_e32 v213, 0x7fffff80, v6
	v_not_b32_e32 v214, v6
	v_or_b32_e32 v214, 0x7f, v214
	v_cndmask_b32_e32 v213, v214, v213, vcc
	v_not_b32_e32 v215, v6
	v_and_b32_e32 v215, 0x7f, v215
	ds_write_b32 v217, v213 offset:4608
	ds_write_b8 v216, v215 offset:1152
	v_cmp_gt_i32_e32 vcc, 0, v25
	v_and_b32_e32 v214, 0x7fffff80, v25
	v_not_b32_e32 v215, v25
	v_or_b32_e32 v215, 0x7f, v215
	v_cndmask_b32_e32 v214, v215, v214, vcc
	v_not_b32_e32 v213, v25
	v_and_b32_e32 v213, 0x7f, v213
	ds_write_b32 v217, v214 offset:5120
	ds_write_b8 v216, v213 offset:1280
	v_cmp_gt_i32_e32 vcc, 0, v29
	v_and_b32_e32 v215, 0x7fffff80, v29
	v_not_b32_e32 v213, v29
	v_or_b32_e32 v213, 0x7f, v213
	v_cndmask_b32_e32 v215, v213, v215, vcc
	v_not_b32_e32 v214, v29
	v_and_b32_e32 v214, 0x7f, v214
	ds_write_b32 v217, v215 offset:5632
	ds_write_b8 v216, v214 offset:1408
	v_cmp_gt_i32_e32 vcc, 0, v40
	v_and_b32_e32 v213, 0x7fffff80, v40
	v_not_b32_e32 v214, v40
	v_or_b32_e32 v214, 0x7f, v214
	v_cndmask_b32_e32 v213, v214, v213, vcc
	v_not_b32_e32 v215, v40
	v_and_b32_e32 v215, 0x7f, v215
	ds_write_b32 v217, v213 offset:6144
	ds_write_b8 v216, v215 offset:1536
	v_cmp_gt_i32_e32 vcc, 0, v22
	v_and_b32_e32 v214, 0x7fffff80, v22
	v_not_b32_e32 v215, v22
	v_or_b32_e32 v215, 0x7f, v215
	v_cndmask_b32_e32 v214, v215, v214, vcc
	v_not_b32_e32 v213, v22
	v_and_b32_e32 v213, 0x7f, v213
	ds_write_b32 v217, v214 offset:6656
	ds_write_b8 v216, v213 offset:1664
	v_cmp_gt_i32_e32 vcc, 0, v49
	v_and_b32_e32 v215, 0x7fffff80, v49
	v_not_b32_e32 v213, v49
	v_or_b32_e32 v213, 0x7f, v213
	v_cndmask_b32_e32 v215, v213, v215, vcc
	v_not_b32_e32 v214, v49
	v_and_b32_e32 v214, 0x7f, v214
	ds_write_b32 v217, v215 offset:7168
	ds_write_b8 v216, v214 offset:1792
	v_cmp_gt_i32_e32 vcc, 0, v15
	v_and_b32_e32 v213, 0x7fffff80, v15
	v_not_b32_e32 v214, v15
	v_or_b32_e32 v214, 0x7f, v214
	v_cndmask_b32_e32 v213, v214, v213, vcc
	v_not_b32_e32 v215, v15
	v_and_b32_e32 v215, 0x7f, v215
	ds_write_b32 v217, v213 offset:7680
	ds_write_b8 v216, v215 offset:1920
	s_branch .LBB0_1083
